# loop-edge rotation (loop-control SALU ahead of the closing barrier) re-tried on top of the priority raise, peel and P5 slack filling
# speedup vs baseline: 1.0038x; 1.0038x over previous
; #define PG8_STAGE(bufoff, gbase, voff) do { _Pragma("unroll") for (int _i = 0; _i < 2; ++_i) \
;         __builtin_amdgcn_global_load_lds((const unsigned*)((const char*)(gbase) + (voff)[_i]), (LAS unsigned*)(lds + (bufoff) + ldsw + _i * 8192), 16, 0, 0); } while (0)
; #define PG8_LDA(dst, b, h) do { _Pragma("unroll") for (int m = 0; m < 4; ++m) _Pragma("unroll") for (int k = 0; k < 2; ++k) dst[m][k] = *(const LAS bf16x8*)(lds + PG8_SA(b, h) + aoff + m * 2048 + k * 1024); } while (0)
; #define PG8_LDB(dst, b, h) do { _Pragma("unroll") for (int n = 0; n < 2; ++n) _Pragma("unroll") for (int k = 0; k < 2; ++k) dst[n][k] = *(const LAS bf16x8*)(lds + PG8_SB(b, h) + boff + n * 2048 + k * 1024); } while (0)
; #define PG8_MMA(ai, bj, At, Bt) do { __builtin_amdgcn_s_setprio(1); _Pragma("unroll") for (int m = 0; m < 4; ++m) _Pragma("unroll") for (int n = 0; n < 2; ++n) _Pragma("unroll") for (int k = 0; k < 2; ++k) \
;         acc[ai][bj][m][n] = __builtin_amdgcn_mfma_f32_16x16x32_bf16(Bt[n][k], At[m][k], acc[ai][bj][m][n], 0, 0, 0); __builtin_amdgcn_s_setprio(0); } while (0)
; #define PG8_WAIT_V(n) asm volatile("s_waitcnt vmcnt(" #n ")" ::: "memory")
; #define PG8_WAIT_L(n) asm volatile("s_waitcnt lgkmcnt(" #n ")" ::: "memory")
; #define PG8_BAR __builtin_amdgcn_s_barrier()
; #define PG8_SCHED __builtin_amdgcn_sched_barrier(0)
; template <class Sched, class Epi, bool ALIGN_EPI, bool SP2>
; __device__ __forceinline__ void gemm_phase(LAS unsigned char* lds, const int K, const int lda, const int ldb, const Sched& S, const Epi& E) {
;     ...
;             PG8_LDB(B0, 0, 0); PG8_LDB(B1, 0, 1); PG8_SCHED; PG8_LDA(At, 0, 0); PG8_STAGE(PG8_SA(1, 1), a1 + hstepA, voffA);
;             PG8_WAIT_V(8); PG8_WAIT_L(0); PG8_BAR; PG8_MMA(0, 0, At, B0); PG8_MMA(0, 1, At, B1); PG8_BAR; PG8_SCHED;
;             PG8_LDA(At, 0, 1); PG8_STAGE(PG8_SB(0, 0), b2, voffB); PG8_STAGE(PG8_SB(0, 1), b2 + hstepB, voffB); PG8_STAGE(PG8_SA(0, 0), a2, voffA);
;             PG8_WAIT_V(8); PG8_WAIT_L(0); PG8_BAR; PG8_MMA(1, 0, At, B0); PG8_MMA(1, 1, At, B1); PG8_BAR; PG8_SCHED;
.LBB0_155:
	ds_read_b128 v[140:143], v147
	ds_read_b128 v[150:153], v147 offset:1024
	ds_read_b128 v[154:157], v147 offset:2048
	ds_read_b128 v[158:161], v147 offset:3072
	ds_read_b128 v[162:165], v148
	ds_read_b128 v[166:169], v148 offset:1024
	ds_read_b128 v[170:173], v148 offset:2048
	ds_read_b128 v[180:183], v148 offset:3072
	s_add_u32 s22, s20, 0xfff80080
	s_addc_u32 s23, s21, -1
	s_cmp_eq_u32 s75, 28
	s_cselect_b32 s25, s15, s23
	s_cselect_b32 s24, s14, s22
	s_cselect_b32 s23, s17, s74
	s_cselect_b32 s22, s16, s13
	s_add_i32 m0, s3, 0xc000
	ds_read_b128 v[184:187], v149
	ds_read_b128 v[188:191], v149 offset:1024
	ds_read_b128 v[192:195], v149 offset:2048
	ds_read_b128 v[196:199], v149 offset:3072
	ds_read_b128 v[200:203], v149 offset:4096
	ds_read_b128 v[204:207], v149 offset:5120
	ds_read_b128 v[208:211], v149 offset:6144
	ds_read_b128 v[212:215], v149 offset:7168
	global_load_lds_dwordx4 v136, s[20:21]
	s_add_i32 m0, s3, 0xe000
	s_nop 0
	global_load_lds_dwordx4 v138, s[20:21]
	s_waitcnt vmcnt(8) lgkmcnt(0)
	s_barrier
	v_mfma_f32_16x16x32_bf16 v[124:127], v[140:143], v[184:187], v[124:127]
	v_mfma_f32_16x16x32_bf16 v[120:123], v[154:157], v[184:187], v[120:123]
	v_mfma_f32_16x16x32_bf16 v[108:111], v[140:143], v[192:195], v[108:111]
	v_mfma_f32_16x16x32_bf16 v[104:107], v[154:157], v[192:195], v[104:107]
	v_mfma_f32_16x16x32_bf16 v[92:95], v[140:143], v[200:203], v[92:95]
	v_mfma_f32_16x16x32_bf16 v[88:91], v[154:157], v[200:203], v[88:91]
	v_mfma_f32_16x16x32_bf16 v[76:79], v[140:143], v[208:211], v[76:79]
	v_mfma_f32_16x16x32_bf16 v[72:75], v[154:157], v[208:211], v[72:75]
	v_mfma_f32_16x16x32_bf16 v[124:127], v[150:153], v[188:191], v[124:127]
	v_mfma_f32_16x16x32_bf16 v[120:123], v[158:161], v[188:191], v[120:123]
	v_mfma_f32_16x16x32_bf16 v[108:111], v[150:153], v[196:199], v[108:111]
	v_mfma_f32_16x16x32_bf16 v[104:107], v[158:161], v[196:199], v[104:107]
	v_mfma_f32_16x16x32_bf16 v[92:95], v[150:153], v[204:207], v[92:95]
	v_mfma_f32_16x16x32_bf16 v[88:91], v[158:161], v[204:207], v[88:91]
	v_mfma_f32_16x16x32_bf16 v[76:79], v[150:153], v[212:215], v[76:79]
	v_mfma_f32_16x16x32_bf16 v[72:75], v[158:161], v[212:215], v[72:75]
	v_mfma_f32_16x16x32_bf16 v[116:119], v[162:165], v[184:187], v[116:119]
	v_mfma_f32_16x16x32_bf16 v[112:115], v[170:173], v[184:187], v[112:115]
	v_mfma_f32_16x16x32_bf16 v[100:103], v[162:165], v[192:195], v[100:103]
	v_mfma_f32_16x16x32_bf16 v[96:99], v[170:173], v[192:195], v[96:99]
	v_mfma_f32_16x16x32_bf16 v[84:87], v[162:165], v[200:203], v[84:87]
	v_mfma_f32_16x16x32_bf16 v[80:83], v[170:173], v[200:203], v[80:83]
	v_mfma_f32_16x16x32_bf16 v[68:71], v[162:165], v[208:211], v[68:71]
	v_mfma_f32_16x16x32_bf16 v[64:67], v[170:173], v[208:211], v[64:67]
	v_mfma_f32_16x16x32_bf16 v[116:119], v[166:169], v[188:191], v[116:119]
	v_mfma_f32_16x16x32_bf16 v[112:115], v[180:183], v[188:191], v[112:115]
	v_mfma_f32_16x16x32_bf16 v[100:103], v[166:169], v[196:199], v[100:103]
	v_mfma_f32_16x16x32_bf16 v[96:99], v[180:183], v[196:199], v[96:99]
	v_mfma_f32_16x16x32_bf16 v[84:87], v[166:169], v[204:207], v[84:87]
	v_mfma_f32_16x16x32_bf16 v[80:83], v[180:183], v[204:207], v[80:83]
	v_mfma_f32_16x16x32_bf16 v[68:71], v[166:169], v[212:215], v[68:71]
	v_mfma_f32_16x16x32_bf16 v[64:67], v[180:183], v[212:215], v[64:67]
	s_barrier
	s_add_i32 s78, s35, s2
	v_lshl_add_u64 v[174:175], s[22:23], 0, v[130:131]
	s_mov_b32 m0, s78
	ds_read_b128 v[184:187], v149 offset:16384
	ds_read_b128 v[188:191], v149 offset:17408
	ds_read_b128 v[192:195], v149 offset:18432
	ds_read_b128 v[196:199], v149 offset:19456
	ds_read_b128 v[200:203], v149 offset:20480
	ds_read_b128 v[204:207], v149 offset:21504
	ds_read_b128 v[208:211], v149 offset:22528
	ds_read_b128 v[212:215], v149 offset:23552
	global_load_lds_dwordx4 v[174:175], off
	s_add_i32 m0, s78, 0x2000
	s_add_u32 s78, s22, 0x80000
	v_lshl_add_u64 v[216:217], s[22:23], 0, v[134:135]
	s_addc_u32 s79, s23, 0
	s_add_i32 s84, s50, s2
	global_load_lds_dwordx4 v[216:217], off
	s_mov_b32 m0, s84
	v_lshl_add_u64 v[220:221], s[24:25], 0, v[132:133]
	global_load_lds_dwordx4 v130, s[78:79]
	s_add_i32 m0, s84, 0x2000
	s_nop 0
	global_load_lds_dwordx4 v134, s[78:79]
	v_lshl_add_u64 v[218:219], s[24:25], 0, v[128:129]
	s_mov_b32 m0, s3
	s_nop 0
	global_load_lds_dwordx4 v[218:219], off
	s_mov_b32 m0, s19
	s_nop 0
	global_load_lds_dwordx4 v[220:221], off
	s_waitcnt vmcnt(8) lgkmcnt(0)
	s_barrier
	v_mfma_f32_16x16x32_bf16 v[60:63], v[140:143], v[184:187], v[60:63]
	v_mfma_f32_16x16x32_bf16 v[56:59], v[154:157], v[184:187], v[56:59]
	v_mfma_f32_16x16x32_bf16 v[44:47], v[140:143], v[192:195], v[44:47]
	v_mfma_f32_16x16x32_bf16 v[40:43], v[154:157], v[192:195], v[40:43]
	v_mfma_f32_16x16x32_bf16 v[28:31], v[140:143], v[200:203], v[28:31]
	v_mfma_f32_16x16x32_bf16 v[24:27], v[154:157], v[200:203], v[24:27]
	v_mfma_f32_16x16x32_bf16 v[12:15], v[140:143], v[208:211], v[12:15]
	v_mfma_f32_16x16x32_bf16 v[8:11], v[154:157], v[208:211], v[8:11]
	v_mfma_f32_16x16x32_bf16 v[60:63], v[150:153], v[188:191], v[60:63]
	v_mfma_f32_16x16x32_bf16 v[56:59], v[158:161], v[188:191], v[56:59]
	v_mfma_f32_16x16x32_bf16 v[44:47], v[150:153], v[196:199], v[44:47]
	v_mfma_f32_16x16x32_bf16 v[40:43], v[158:161], v[196:199], v[40:43]
	v_mfma_f32_16x16x32_bf16 v[28:31], v[150:153], v[204:207], v[28:31]
	v_mfma_f32_16x16x32_bf16 v[24:27], v[158:161], v[204:207], v[24:27]
	v_mfma_f32_16x16x32_bf16 v[12:15], v[150:153], v[212:215], v[12:15]
	v_mfma_f32_16x16x32_bf16 v[8:11], v[158:161], v[212:215], v[8:11]
	v_mfma_f32_16x16x32_bf16 v[52:55], v[162:165], v[184:187], v[52:55]
	v_mfma_f32_16x16x32_bf16 v[48:51], v[170:173], v[184:187], v[48:51]
	v_mfma_f32_16x16x32_bf16 v[36:39], v[162:165], v[192:195], v[36:39]
	v_mfma_f32_16x16x32_bf16 v[32:35], v[170:173], v[192:195], v[32:35]
	v_mfma_f32_16x16x32_bf16 v[20:23], v[162:165], v[200:203], v[20:23]
	v_mfma_f32_16x16x32_bf16 v[16:19], v[170:173], v[200:203], v[16:19]
	v_mfma_f32_16x16x32_bf16 v[4:7], v[162:165], v[208:211], v[4:7]
	v_mfma_f32_16x16x32_bf16 v[0:3], v[170:173], v[208:211], v[0:3]
	v_mfma_f32_16x16x32_bf16 v[52:55], v[166:169], v[188:191], v[52:55]
	v_mfma_f32_16x16x32_bf16 v[48:51], v[180:183], v[188:191], v[48:51]
	v_mfma_f32_16x16x32_bf16 v[36:39], v[166:169], v[196:199], v[36:39]
	v_mfma_f32_16x16x32_bf16 v[32:35], v[180:183], v[196:199], v[32:35]
	v_mfma_f32_16x16x32_bf16 v[20:23], v[166:169], v[204:207], v[20:23]
	v_mfma_f32_16x16x32_bf16 v[16:19], v[180:183], v[204:207], v[16:19]
	v_mfma_f32_16x16x32_bf16 v[4:7], v[166:169], v[212:215], v[4:7]
	v_mfma_f32_16x16x32_bf16 v[0:3], v[180:183], v[212:215], v[0:3]
	s_barrier
; #define PG8_STAGE(bufoff, gbase, voff) do { _Pragma("unroll") for (int _i = 0; _i < 2; ++_i) \
;         __builtin_amdgcn_global_load_lds((const unsigned*)((const char*)(gbase) + (voff)[_i]), (LAS unsigned*)(lds + (bufoff) + ldsw + _i * 8192), 16, 0, 0); } while (0)
; #define PG8_LDA(dst, b, h) do { _Pragma("unroll") for (int m = 0; m < 4; ++m) _Pragma("unroll") for (int k = 0; k < 2; ++k) dst[m][k] = *(const LAS bf16x8*)(lds + PG8_SA(b, h) + aoff + m * 2048 + k * 1024); } while (0)
; #define PG8_LDB(dst, b, h) do { _Pragma("unroll") for (int n = 0; n < 2; ++n) _Pragma("unroll") for (int k = 0; k < 2; ++k) dst[n][k] = *(const LAS bf16x8*)(lds + PG8_SB(b, h) + boff + n * 2048 + k * 1024); } while (0)
; #define PG8_MMA(ai, bj, At, Bt) do { __builtin_amdgcn_s_setprio(1); _Pragma("unroll") for (int m = 0; m < 4; ++m) _Pragma("unroll") for (int n = 0; n < 2; ++n) _Pragma("unroll") for (int k = 0; k < 2; ++k) \
;         acc[ai][bj][m][n] = __builtin_amdgcn_mfma_f32_16x16x32_bf16(Bt[n][k], At[m][k], acc[ai][bj][m][n], 0, 0, 0); __builtin_amdgcn_s_setprio(0); } while (0)
; #define PG8_WAIT_V(n) asm volatile("s_waitcnt vmcnt(" #n ")" ::: "memory")
; #define PG8_WAIT_L(n) asm volatile("s_waitcnt lgkmcnt(" #n ")" ::: "memory")
; #define PG8_BAR __builtin_amdgcn_s_barrier()
; template <class Sched, class Epi, bool ALIGN_EPI, bool SP2>
; __device__ __forceinline__ void gemm_phase(LAS unsigned char* lds, const int K, const int lda, const int ldb, const Sched& S, const Epi& E) {
;     ...
;         for (int t = 0; t < nt; t += 2) {
;             const bool last = (t == nt - 2);
;             const char* a1 = cA + (size_t)(t + 1) * kstep;
;             const char* a2 = last ? nA : cA + (size_t)(t + 2) * kstep; const char* b2 = last ? nB : cB + (size_t)(t + 2) * kstep;
;             const char* a3 = a2 + kstep; const char* b3 = b2 + kstep;
;     ...
;             PG8_LDB(B0, 1, 0); PG8_LDB(B1, 1, 1); PG8_SCHED; PG8_LDA(At, 1, 0); PG8_STAGE(PG8_SA(0, 1), a2 + hstepA, voffA);
;             PG8_WAIT_V(8); PG8_WAIT_L(0); PG8_BAR; PG8_MMA(0, 0, At, B0); PG8_MMA(0, 1, At, B1); PG8_BAR; PG8_SCHED;
;             PG8_LDA(At, 1, 1); PG8_STAGE(PG8_SB(1, 0), b3, voffB); PG8_STAGE(PG8_SB(1, 1), b3 + hstepB, voffB); PG8_STAGE(PG8_SA(1, 0), a3, voffA);
;             PG8_WAIT_V(8); PG8_WAIT_L(0); PG8_BAR; PG8_MMA(1, 0, At, B0); PG8_MMA(1, 1, At, B1); PG8_BAR; PG8_SCHED;
	s_add_i32 s78, 0, 0x18000
	s_add_i32 s79, 0, 0x1c000
	v_add_u32_e32 v158, s78, v145
	v_add_u32_e32 v177, s79, v145
	ds_read_b128 v[140:143], v158
	ds_read_b128 v[150:153], v158 offset:1024
	ds_read_b128 v[154:157], v158 offset:2048
	ds_read_b128 v[158:161], v158 offset:3072
	ds_read_b128 v[162:165], v177
	ds_read_b128 v[166:169], v177 offset:1024
	ds_read_b128 v[170:173], v177 offset:2048
	ds_read_b128 v[180:183], v177 offset:3072
	s_add_u32 s24, s24, 0x80000
	s_addc_u32 s25, s25, 0
	s_mov_b32 m0, s26
	ds_read_b128 v[184:187], v149 offset:32768
	ds_read_b128 v[188:191], v149 offset:33792
	ds_read_b128 v[192:195], v149 offset:34816
	ds_read_b128 v[196:199], v149 offset:35840
	ds_read_b128 v[200:203], v149 offset:36864
	ds_read_b128 v[204:207], v149 offset:37888
	ds_read_b128 v[208:211], v149 offset:38912
	ds_read_b128 v[212:215], v149 offset:39936
	global_load_lds_dwordx4 v128, s[24:25]
	s_mov_b32 m0, s27
	s_nop 0
	global_load_lds_dwordx4 v132, s[24:25]
	s_waitcnt vmcnt(8) lgkmcnt(0)
	s_barrier
	v_mfma_f32_16x16x32_bf16 v[124:127], v[140:143], v[184:187], v[124:127]
	v_mfma_f32_16x16x32_bf16 v[120:123], v[154:157], v[184:187], v[120:123]
	v_mfma_f32_16x16x32_bf16 v[108:111], v[140:143], v[192:195], v[108:111]
	v_mfma_f32_16x16x32_bf16 v[104:107], v[154:157], v[192:195], v[104:107]
	v_mfma_f32_16x16x32_bf16 v[92:95], v[140:143], v[200:203], v[92:95]
	v_mfma_f32_16x16x32_bf16 v[88:91], v[154:157], v[200:203], v[88:91]
	v_mfma_f32_16x16x32_bf16 v[76:79], v[140:143], v[208:211], v[76:79]
	v_mfma_f32_16x16x32_bf16 v[72:75], v[154:157], v[208:211], v[72:75]
	v_mfma_f32_16x16x32_bf16 v[124:127], v[150:153], v[188:191], v[124:127]
	v_mfma_f32_16x16x32_bf16 v[120:123], v[158:161], v[188:191], v[120:123]
	v_mfma_f32_16x16x32_bf16 v[108:111], v[150:153], v[196:199], v[108:111]
	v_mfma_f32_16x16x32_bf16 v[104:107], v[158:161], v[196:199], v[104:107]
	v_mfma_f32_16x16x32_bf16 v[92:95], v[150:153], v[204:207], v[92:95]
	v_mfma_f32_16x16x32_bf16 v[88:91], v[158:161], v[204:207], v[88:91]
	v_mfma_f32_16x16x32_bf16 v[76:79], v[150:153], v[212:215], v[76:79]
	v_mfma_f32_16x16x32_bf16 v[72:75], v[158:161], v[212:215], v[72:75]
	v_mfma_f32_16x16x32_bf16 v[116:119], v[162:165], v[184:187], v[116:119]
	v_mfma_f32_16x16x32_bf16 v[112:115], v[170:173], v[184:187], v[112:115]
	v_mfma_f32_16x16x32_bf16 v[100:103], v[162:165], v[192:195], v[100:103]
	v_mfma_f32_16x16x32_bf16 v[96:99], v[170:173], v[192:195], v[96:99]
	v_mfma_f32_16x16x32_bf16 v[84:87], v[162:165], v[200:203], v[84:87]
	v_mfma_f32_16x16x32_bf16 v[80:83], v[170:173], v[200:203], v[80:83]
	v_mfma_f32_16x16x32_bf16 v[68:71], v[162:165], v[208:211], v[68:71]
	v_mfma_f32_16x16x32_bf16 v[64:67], v[170:173], v[208:211], v[64:67]
	v_mfma_f32_16x16x32_bf16 v[116:119], v[166:169], v[188:191], v[116:119]
	v_mfma_f32_16x16x32_bf16 v[112:115], v[180:183], v[188:191], v[112:115]
	v_mfma_f32_16x16x32_bf16 v[100:103], v[166:169], v[196:199], v[100:103]
	v_mfma_f32_16x16x32_bf16 v[96:99], v[180:183], v[196:199], v[96:99]
	v_mfma_f32_16x16x32_bf16 v[84:87], v[166:169], v[204:207], v[84:87]
	v_mfma_f32_16x16x32_bf16 v[80:83], v[180:183], v[204:207], v[80:83]
	v_mfma_f32_16x16x32_bf16 v[68:71], v[166:169], v[212:215], v[68:71]
	v_mfma_f32_16x16x32_bf16 v[64:67], v[180:183], v[212:215], v[64:67]
	s_barrier
	s_add_i32 s24, s78, s2
	v_lshl_add_u64 v[174:175], v[174:175], 0, s[4:5]
	s_mov_b32 m0, s24
	ds_read_b128 v[184:187], v149 offset:49152
	ds_read_b128 v[188:191], v149 offset:50176
	ds_read_b128 v[192:195], v149 offset:51200
	ds_read_b128 v[196:199], v149 offset:52224
	ds_read_b128 v[200:203], v149 offset:53248
	ds_read_b128 v[204:207], v149 offset:54272
	ds_read_b128 v[208:211], v149 offset:55296
	ds_read_b128 v[212:215], v149 offset:56320
	global_load_lds_dwordx4 v[174:175], off
	s_add_i32 m0, s24, 0x2000
	s_add_u32 s22, s22, 0x80080
	v_lshl_add_u64 v[174:175], v[216:217], 0, s[4:5]
	s_addc_u32 s23, s23, 0
	s_add_i32 s24, s79, s2
	global_load_lds_dwordx4 v[174:175], off
	s_mov_b32 m0, s24
	s_nop 0
	global_load_lds_dwordx4 v130, s[22:23]
	s_add_i32 m0, s24, 0x2000
	s_nop 0
	global_load_lds_dwordx4 v134, s[22:23]
	v_lshl_add_u64 v[174:175], v[218:219], 0, s[4:5]
	s_mov_b32 m0, s29
	s_nop 0
	global_load_lds_dwordx4 v[174:175], off
	v_lshl_add_u64 v[174:175], v[220:221], 0, s[4:5]
	s_mov_b32 m0, s33
	s_nop 0
	global_load_lds_dwordx4 v[174:175], off
	s_waitcnt vmcnt(8) lgkmcnt(0)
	s_barrier
	v_mfma_f32_16x16x32_bf16 v[60:63], v[140:143], v[184:187], v[60:63]
	v_mfma_f32_16x16x32_bf16 v[56:59], v[154:157], v[184:187], v[56:59]
	v_mfma_f32_16x16x32_bf16 v[44:47], v[140:143], v[192:195], v[44:47]
	v_mfma_f32_16x16x32_bf16 v[40:43], v[154:157], v[192:195], v[40:43]
	v_mfma_f32_16x16x32_bf16 v[28:31], v[140:143], v[200:203], v[28:31]
	v_mfma_f32_16x16x32_bf16 v[24:27], v[154:157], v[200:203], v[24:27]
	v_mfma_f32_16x16x32_bf16 v[12:15], v[140:143], v[208:211], v[12:15]
	v_mfma_f32_16x16x32_bf16 v[8:11], v[154:157], v[208:211], v[8:11]
	v_mfma_f32_16x16x32_bf16 v[60:63], v[150:153], v[188:191], v[60:63]
	v_mfma_f32_16x16x32_bf16 v[56:59], v[158:161], v[188:191], v[56:59]
	v_mfma_f32_16x16x32_bf16 v[44:47], v[150:153], v[196:199], v[44:47]
	v_mfma_f32_16x16x32_bf16 v[40:43], v[158:161], v[196:199], v[40:43]
	v_mfma_f32_16x16x32_bf16 v[28:31], v[150:153], v[204:207], v[28:31]
	v_mfma_f32_16x16x32_bf16 v[24:27], v[158:161], v[204:207], v[24:27]
	v_mfma_f32_16x16x32_bf16 v[12:15], v[150:153], v[212:215], v[12:15]
	v_mfma_f32_16x16x32_bf16 v[8:11], v[158:161], v[212:215], v[8:11]
	v_mfma_f32_16x16x32_bf16 v[52:55], v[162:165], v[184:187], v[52:55]
	v_mfma_f32_16x16x32_bf16 v[48:51], v[170:173], v[184:187], v[48:51]
	v_mfma_f32_16x16x32_bf16 v[36:39], v[162:165], v[192:195], v[36:39]
	v_mfma_f32_16x16x32_bf16 v[32:35], v[170:173], v[192:195], v[32:35]
	v_mfma_f32_16x16x32_bf16 v[20:23], v[162:165], v[200:203], v[20:23]
	v_mfma_f32_16x16x32_bf16 v[16:19], v[170:173], v[200:203], v[16:19]
	v_mfma_f32_16x16x32_bf16 v[4:7], v[162:165], v[208:211], v[4:7]
	v_mfma_f32_16x16x32_bf16 v[0:3], v[170:173], v[208:211], v[0:3]
	v_mfma_f32_16x16x32_bf16 v[52:55], v[166:169], v[188:191], v[52:55]
	v_mfma_f32_16x16x32_bf16 v[48:51], v[180:183], v[188:191], v[48:51]
	v_mfma_f32_16x16x32_bf16 v[36:39], v[166:169], v[196:199], v[36:39]
	v_mfma_f32_16x16x32_bf16 v[32:35], v[180:183], v[196:199], v[32:35]
	v_mfma_f32_16x16x32_bf16 v[20:23], v[166:169], v[204:207], v[20:23]
	v_mfma_f32_16x16x32_bf16 v[16:19], v[180:183], v[204:207], v[16:19]
	v_mfma_f32_16x16x32_bf16 v[4:7], v[166:169], v[212:215], v[4:7]
	v_mfma_f32_16x16x32_bf16 v[0:3], v[180:183], v[212:215], v[0:3]
	s_add_i32 s75, s75, 2
	s_add_u32 s20, s20, 0x100
	s_addc_u32 s21, s21, 0
	s_add_u32 s13, s13, 0x100
	s_addc_u32 s74, s74, 0
	s_cmp_gt_u32 s75, 29
	s_barrier
	s_cbranch_scc0 .LBB0_155
	s_setprio 0
	s_and_b64 vcc, exec, s[6:7]
	s_cbranch_vccz .LBB0_158
	s_barrier

; #define PG8_STAGE(bufoff, gbase, voff) do { _Pragma("unroll") for (int _i = 0; _i < 2; ++_i) \
;         __builtin_amdgcn_global_load_lds((const unsigned*)((const char*)(gbase) + (voff)[_i]), (LAS unsigned*)(lds + (bufoff) + ldsw + _i * 8192), 16, 0, 0); } while (0)
; #define PG8_LDA(dst, b, h) do { _Pragma("unroll") for (int m = 0; m < 4; ++m) _Pragma("unroll") for (int k = 0; k < 2; ++k) dst[m][k] = *(const LAS bf16x8*)(lds + PG8_SA(b, h) + aoff + m * 2048 + k * 1024); } while (0)
; #define PG8_LDB(dst, b, h) do { _Pragma("unroll") for (int n = 0; n < 2; ++n) _Pragma("unroll") for (int k = 0; k < 2; ++k) dst[n][k] = *(const LAS bf16x8*)(lds + PG8_SB(b, h) + boff + n * 2048 + k * 1024); } while (0)
; #define PG8_MMA(ai, bj, At, Bt) do { __builtin_amdgcn_s_setprio(1); _Pragma("unroll") for (int m = 0; m < 4; ++m) _Pragma("unroll") for (int n = 0; n < 2; ++n) _Pragma("unroll") for (int k = 0; k < 2; ++k) \
;         acc[ai][bj][m][n] = __builtin_amdgcn_mfma_f32_16x16x32_bf16(Bt[n][k], At[m][k], acc[ai][bj][m][n], 0, 0, 0); __builtin_amdgcn_s_setprio(0); } while (0)
; #define PG8_WAIT_V(n) asm volatile("s_waitcnt vmcnt(" #n ")" ::: "memory")
; #define PG8_WAIT_L(n) asm volatile("s_waitcnt lgkmcnt(" #n ")" ::: "memory")
; #define PG8_BAR __builtin_amdgcn_s_barrier()
; #define PG8_SCHED __builtin_amdgcn_sched_barrier(0)
; template <class Sched, class Epi, bool ALIGN_EPI, bool SP2>
; __device__ __forceinline__ void gemm_phase(LAS unsigned char* lds, const int K, const int lda, const int ldb, const Sched& S, const Epi& E) {
;     ...
;             PG8_LDB(B0, 0, 0); PG8_LDB(B1, 0, 1); PG8_SCHED; PG8_LDA(At, 0, 0); PG8_STAGE(PG8_SA(1, 1), a1 + hstepA, voffA);
;             PG8_WAIT_V(8); PG8_WAIT_L(0); PG8_BAR; PG8_MMA(0, 0, At, B0); PG8_MMA(0, 1, At, B1); PG8_BAR; PG8_SCHED;
;             PG8_LDA(At, 0, 1); PG8_STAGE(PG8_SB(0, 0), b2, voffB); PG8_STAGE(PG8_SB(0, 1), b2 + hstepB, voffB); PG8_STAGE(PG8_SA(0, 0), a2, voffA);
;             PG8_WAIT_V(8); PG8_WAIT_L(0); PG8_BAR; PG8_MMA(1, 0, At, B0); PG8_MMA(1, 1, At, B1); PG8_BAR; PG8_SCHED;
.LBB0_243:
	ds_read_b128 v[124:127], v169
	ds_read_b128 v[132:135], v169 offset:1024
	ds_read_b128 v[136:139], v169 offset:2048
	ds_read_b128 v[140:143], v169 offset:3072
	ds_read_b128 v[144:147], v170
	ds_read_b128 v[156:159], v170 offset:1024
	ds_read_b128 v[160:163], v170 offset:2048
	ds_read_b128 v[182:185], v170 offset:3072
	s_add_u32 s22, s20, 0x100
	s_addc_u32 s23, s21, 0
	s_cmpk_eq_i32 s91, 0x54
	s_cselect_b32 s27, s17, s23
	s_cselect_b32 s26, s16, s22
	s_cselect_b32 s25, s19, s90
	s_cselect_b32 s24, s18, s89
	s_mov_b32 m0, s78
	ds_read_b128 v[186:189], v171
	ds_read_b128 v[190:193], v171 offset:1024
	ds_read_b128 v[194:197], v171 offset:2048
	ds_read_b128 v[198:201], v171 offset:3072
	ds_read_b128 v[202:205], v171 offset:4096
	ds_read_b128 v[206:209], v171 offset:5120
	ds_read_b128 v[210:213], v171 offset:6144
	ds_read_b128 v[214:217], v171 offset:7168
	global_load_lds_dwordx4 v152, s[20:21]
	s_mov_b32 m0, s79
	s_nop 0
	global_load_lds_dwordx4 v154, s[20:21]
	s_waitcnt vmcnt(8) lgkmcnt(0)
	s_barrier
	v_mfma_f32_16x16x32_bf16 v[128:131], v[124:127], v[186:189], v[128:131]
	v_mfma_f32_16x16x32_bf16 v[120:123], v[136:139], v[186:189], v[120:123]
	v_mfma_f32_16x16x32_bf16 v[108:111], v[124:127], v[194:197], v[108:111]
	v_mfma_f32_16x16x32_bf16 v[104:107], v[136:139], v[194:197], v[104:107]
	v_mfma_f32_16x16x32_bf16 v[92:95], v[124:127], v[202:205], v[92:95]
	v_mfma_f32_16x16x32_bf16 v[88:91], v[136:139], v[202:205], v[88:91]
	v_mfma_f32_16x16x32_bf16 v[76:79], v[124:127], v[210:213], v[76:79]
	v_mfma_f32_16x16x32_bf16 v[72:75], v[136:139], v[210:213], v[72:75]
	v_mfma_f32_16x16x32_bf16 v[128:131], v[132:135], v[190:193], v[128:131]
	v_mfma_f32_16x16x32_bf16 v[120:123], v[140:143], v[190:193], v[120:123]
	v_mfma_f32_16x16x32_bf16 v[108:111], v[132:135], v[198:201], v[108:111]
	v_mfma_f32_16x16x32_bf16 v[104:107], v[140:143], v[198:201], v[104:107]
	v_mfma_f32_16x16x32_bf16 v[92:95], v[132:135], v[206:209], v[92:95]
	v_mfma_f32_16x16x32_bf16 v[88:91], v[140:143], v[206:209], v[88:91]
	v_mfma_f32_16x16x32_bf16 v[76:79], v[132:135], v[214:217], v[76:79]
	v_mfma_f32_16x16x32_bf16 v[72:75], v[140:143], v[214:217], v[72:75]
	v_mfma_f32_16x16x32_bf16 v[116:119], v[144:147], v[186:189], v[116:119]
	v_mfma_f32_16x16x32_bf16 v[112:115], v[160:163], v[186:189], v[112:115]
	v_mfma_f32_16x16x32_bf16 v[100:103], v[144:147], v[194:197], v[100:103]
	v_mfma_f32_16x16x32_bf16 v[96:99], v[160:163], v[194:197], v[96:99]
	v_mfma_f32_16x16x32_bf16 v[84:87], v[144:147], v[202:205], v[84:87]
	v_mfma_f32_16x16x32_bf16 v[80:83], v[160:163], v[202:205], v[80:83]
	v_mfma_f32_16x16x32_bf16 v[68:71], v[144:147], v[210:213], v[68:71]
	v_mfma_f32_16x16x32_bf16 v[64:67], v[160:163], v[210:213], v[64:67]
	v_mfma_f32_16x16x32_bf16 v[116:119], v[156:159], v[190:193], v[116:119]
	v_mfma_f32_16x16x32_bf16 v[112:115], v[182:185], v[190:193], v[112:115]
	v_mfma_f32_16x16x32_bf16 v[100:103], v[156:159], v[198:201], v[100:103]
	v_mfma_f32_16x16x32_bf16 v[96:99], v[182:185], v[198:201], v[96:99]
	v_mfma_f32_16x16x32_bf16 v[84:87], v[156:159], v[206:209], v[84:87]
	v_mfma_f32_16x16x32_bf16 v[80:83], v[182:185], v[206:209], v[80:83]
	v_mfma_f32_16x16x32_bf16 v[68:71], v[156:159], v[214:217], v[68:71]
	v_mfma_f32_16x16x32_bf16 v[64:67], v[182:185], v[214:217], v[64:67]
	s_barrier
	s_mov_b32 m0, s84
	v_lshl_add_u64 v[164:165], s[24:25], 0, v[148:149]
	ds_read_b128 v[186:189], v171 offset:16384
	ds_read_b128 v[190:193], v171 offset:17408
	ds_read_b128 v[194:197], v171 offset:18432
	ds_read_b128 v[198:201], v171 offset:19456
	ds_read_b128 v[202:205], v171 offset:20480
	ds_read_b128 v[206:209], v171 offset:21504
	ds_read_b128 v[210:213], v171 offset:22528
	ds_read_b128 v[214:217], v171 offset:23552
	global_load_lds_dwordx4 v[164:165], off
	s_add_i32 m0, s84, 0x2000
	s_add_u32 s20, s24, 0x160000
	v_lshl_add_u64 v[174:175], s[24:25], 0, v[150:151]
	s_addc_u32 s21, s25, 0
	s_add_i32 s96, s53, s13
	global_load_lds_dwordx4 v[174:175], off
	s_mov_b32 m0, s96
	v_lshl_add_u64 v[220:221], s[26:27], 0, v[150:151]
	global_load_lds_dwordx4 v148, s[20:21]
	s_add_i32 m0, s96, 0x2000
	s_nop 0
	global_load_lds_dwordx4 v150, s[20:21]
	v_lshl_add_u64 v[218:219], s[26:27], 0, v[148:149]
	s_mov_b32 m0, s28
	s_nop 0
	global_load_lds_dwordx4 v[218:219], off
	s_mov_b32 m0, s29
	s_nop 0
	global_load_lds_dwordx4 v[220:221], off
	s_waitcnt vmcnt(8) lgkmcnt(0)
	s_barrier
	v_mfma_f32_16x16x32_bf16 v[60:63], v[124:127], v[186:189], v[60:63]
	v_mfma_f32_16x16x32_bf16 v[56:59], v[136:139], v[186:189], v[56:59]
	v_mfma_f32_16x16x32_bf16 v[44:47], v[124:127], v[194:197], v[44:47]
	v_mfma_f32_16x16x32_bf16 v[40:43], v[136:139], v[194:197], v[40:43]
	v_mfma_f32_16x16x32_bf16 v[28:31], v[124:127], v[202:205], v[28:31]
	v_mfma_f32_16x16x32_bf16 v[24:27], v[136:139], v[202:205], v[24:27]
	v_mfma_f32_16x16x32_bf16 v[12:15], v[124:127], v[210:213], v[12:15]
	v_mfma_f32_16x16x32_bf16 v[8:11], v[136:139], v[210:213], v[8:11]
	v_mfma_f32_16x16x32_bf16 v[60:63], v[132:135], v[190:193], v[60:63]
	v_mfma_f32_16x16x32_bf16 v[56:59], v[140:143], v[190:193], v[56:59]
	v_mfma_f32_16x16x32_bf16 v[44:47], v[132:135], v[198:201], v[44:47]
	v_mfma_f32_16x16x32_bf16 v[40:43], v[140:143], v[198:201], v[40:43]
	v_mfma_f32_16x16x32_bf16 v[28:31], v[132:135], v[206:209], v[28:31]
	v_mfma_f32_16x16x32_bf16 v[24:27], v[140:143], v[206:209], v[24:27]
	v_mfma_f32_16x16x32_bf16 v[12:15], v[132:135], v[214:217], v[12:15]
	v_mfma_f32_16x16x32_bf16 v[8:11], v[140:143], v[214:217], v[8:11]
	v_mfma_f32_16x16x32_bf16 v[52:55], v[144:147], v[186:189], v[52:55]
	v_mfma_f32_16x16x32_bf16 v[48:51], v[160:163], v[186:189], v[48:51]
	v_mfma_f32_16x16x32_bf16 v[36:39], v[144:147], v[194:197], v[36:39]
	v_mfma_f32_16x16x32_bf16 v[32:35], v[160:163], v[194:197], v[32:35]
	v_mfma_f32_16x16x32_bf16 v[20:23], v[144:147], v[202:205], v[20:23]
	v_mfma_f32_16x16x32_bf16 v[16:19], v[160:163], v[202:205], v[16:19]
	v_mfma_f32_16x16x32_bf16 v[4:7], v[144:147], v[210:213], v[4:7]
	v_mfma_f32_16x16x32_bf16 v[0:3], v[160:163], v[210:213], v[0:3]
	v_mfma_f32_16x16x32_bf16 v[52:55], v[156:159], v[190:193], v[52:55]
	v_mfma_f32_16x16x32_bf16 v[48:51], v[182:185], v[190:193], v[48:51]
	v_mfma_f32_16x16x32_bf16 v[36:39], v[156:159], v[198:201], v[36:39]
	v_mfma_f32_16x16x32_bf16 v[32:35], v[182:185], v[198:201], v[32:35]
	v_mfma_f32_16x16x32_bf16 v[20:23], v[156:159], v[206:209], v[20:23]
	v_mfma_f32_16x16x32_bf16 v[16:19], v[182:185], v[206:209], v[16:19]
	v_mfma_f32_16x16x32_bf16 v[4:7], v[156:159], v[214:217], v[4:7]
	v_mfma_f32_16x16x32_bf16 v[0:3], v[182:185], v[214:217], v[0:3]
	s_barrier
; #define PG8_STAGE(bufoff, gbase, voff) do { _Pragma("unroll") for (int _i = 0; _i < 2; ++_i) \
;         __builtin_amdgcn_global_load_lds((const unsigned*)((const char*)(gbase) + (voff)[_i]), (LAS unsigned*)(lds + (bufoff) + ldsw + _i * 8192), 16, 0, 0); } while (0)
; #define PG8_LDA(dst, b, h) do { _Pragma("unroll") for (int m = 0; m < 4; ++m) _Pragma("unroll") for (int k = 0; k < 2; ++k) dst[m][k] = *(const LAS bf16x8*)(lds + PG8_SA(b, h) + aoff + m * 2048 + k * 1024); } while (0)
; #define PG8_LDB(dst, b, h) do { _Pragma("unroll") for (int n = 0; n < 2; ++n) _Pragma("unroll") for (int k = 0; k < 2; ++k) dst[n][k] = *(const LAS bf16x8*)(lds + PG8_SB(b, h) + boff + n * 2048 + k * 1024); } while (0)
; #define PG8_MMA(ai, bj, At, Bt) do { __builtin_amdgcn_s_setprio(1); _Pragma("unroll") for (int m = 0; m < 4; ++m) _Pragma("unroll") for (int n = 0; n < 2; ++n) _Pragma("unroll") for (int k = 0; k < 2; ++k) \
;         acc[ai][bj][m][n] = __builtin_amdgcn_mfma_f32_16x16x32_bf16(Bt[n][k], At[m][k], acc[ai][bj][m][n], 0, 0, 0); __builtin_amdgcn_s_setprio(0); } while (0)
; #define PG8_WAIT_V(n) asm volatile("s_waitcnt vmcnt(" #n ")" ::: "memory")
; #define PG8_WAIT_L(n) asm volatile("s_waitcnt lgkmcnt(" #n ")" ::: "memory")
; #define PG8_BAR __builtin_amdgcn_s_barrier()
; template <class Sched, class Epi, bool ALIGN_EPI, bool SP2>
; __device__ __forceinline__ void gemm_phase(LAS unsigned char* lds, const int K, const int lda, const int ldb, const Sched& S, const Epi& E) {
;     ...
;         for (int t = 0; t < nt; t += 2) {
;             const bool last = (t == nt - 2);
;             const char* a1 = cA + (size_t)(t + 1) * kstep;
;             const char* a2 = last ? nA : cA + (size_t)(t + 2) * kstep; const char* b2 = last ? nB : cB + (size_t)(t + 2) * kstep;
;             const char* a3 = a2 + kstep; const char* b3 = b2 + kstep;
;     ...
;             PG8_LDB(B0, 1, 0); PG8_LDB(B1, 1, 1); PG8_SCHED; PG8_LDA(At, 1, 0); PG8_STAGE(PG8_SA(0, 1), a2 + hstepA, voffA);
;             PG8_WAIT_V(8); PG8_WAIT_L(0); PG8_BAR; PG8_MMA(0, 0, At, B0); PG8_MMA(0, 1, At, B1); PG8_BAR; PG8_SCHED;
;             PG8_LDA(At, 1, 1); PG8_STAGE(PG8_SB(1, 0), b3, voffB); PG8_STAGE(PG8_SB(1, 1), b3 + hstepB, voffB); PG8_STAGE(PG8_SA(1, 0), a3, voffA);
;             PG8_WAIT_V(8); PG8_WAIT_L(0); PG8_BAR; PG8_MMA(1, 0, At, B0); PG8_MMA(1, 1, At, B1); PG8_BAR; PG8_SCHED;
	s_add_i32 s96, 0, 0x18000
	s_add_i32 s97, 0, 0x1c000
	v_add_u32_e32 v140, s96, v167
	v_add_u32_e32 v173, s97, v167
	ds_read_b128 v[124:127], v140
	ds_read_b128 v[132:135], v140 offset:1024
	ds_read_b128 v[136:139], v140 offset:2048
	ds_read_b128 v[140:143], v140 offset:3072
	ds_read_b128 v[144:147], v173
	ds_read_b128 v[156:159], v173 offset:1024
	ds_read_b128 v[160:163], v173 offset:2048
	ds_read_b128 v[182:185], v173 offset:3072
	s_add_u32 s20, s26, 0x160000
	s_addc_u32 s21, s27, 0
	s_mov_b32 m0, s33
	ds_read_b128 v[186:189], v171 offset:32768
	ds_read_b128 v[190:193], v171 offset:33792
	ds_read_b128 v[194:197], v171 offset:34816
	ds_read_b128 v[198:201], v171 offset:35840
	ds_read_b128 v[202:205], v171 offset:36864
	ds_read_b128 v[206:209], v171 offset:37888
	ds_read_b128 v[210:213], v171 offset:38912
	ds_read_b128 v[214:217], v171 offset:39936
	global_load_lds_dwordx4 v148, s[20:21]
	s_mov_b32 m0, s35
	s_nop 0
	global_load_lds_dwordx4 v150, s[20:21]
	s_waitcnt vmcnt(8) lgkmcnt(0)
	s_barrier
	v_mfma_f32_16x16x32_bf16 v[128:131], v[124:127], v[186:189], v[128:131]
	v_mfma_f32_16x16x32_bf16 v[120:123], v[136:139], v[186:189], v[120:123]
	v_mfma_f32_16x16x32_bf16 v[108:111], v[124:127], v[194:197], v[108:111]
	v_mfma_f32_16x16x32_bf16 v[104:107], v[136:139], v[194:197], v[104:107]
	v_mfma_f32_16x16x32_bf16 v[92:95], v[124:127], v[202:205], v[92:95]
	v_mfma_f32_16x16x32_bf16 v[88:91], v[136:139], v[202:205], v[88:91]
	v_mfma_f32_16x16x32_bf16 v[76:79], v[124:127], v[210:213], v[76:79]
	v_mfma_f32_16x16x32_bf16 v[72:75], v[136:139], v[210:213], v[72:75]
	v_mfma_f32_16x16x32_bf16 v[128:131], v[132:135], v[190:193], v[128:131]
	v_mfma_f32_16x16x32_bf16 v[120:123], v[140:143], v[190:193], v[120:123]
	v_mfma_f32_16x16x32_bf16 v[108:111], v[132:135], v[198:201], v[108:111]
	v_mfma_f32_16x16x32_bf16 v[104:107], v[140:143], v[198:201], v[104:107]
	v_mfma_f32_16x16x32_bf16 v[92:95], v[132:135], v[206:209], v[92:95]
	v_mfma_f32_16x16x32_bf16 v[88:91], v[140:143], v[206:209], v[88:91]
	v_mfma_f32_16x16x32_bf16 v[76:79], v[132:135], v[214:217], v[76:79]
	v_mfma_f32_16x16x32_bf16 v[72:75], v[140:143], v[214:217], v[72:75]
	v_mfma_f32_16x16x32_bf16 v[116:119], v[144:147], v[186:189], v[116:119]
	v_mfma_f32_16x16x32_bf16 v[112:115], v[160:163], v[186:189], v[112:115]
	v_mfma_f32_16x16x32_bf16 v[100:103], v[144:147], v[194:197], v[100:103]
	v_mfma_f32_16x16x32_bf16 v[96:99], v[160:163], v[194:197], v[96:99]
	v_mfma_f32_16x16x32_bf16 v[84:87], v[144:147], v[202:205], v[84:87]
	v_mfma_f32_16x16x32_bf16 v[80:83], v[160:163], v[202:205], v[80:83]
	v_mfma_f32_16x16x32_bf16 v[68:71], v[144:147], v[210:213], v[68:71]
	v_mfma_f32_16x16x32_bf16 v[64:67], v[160:163], v[210:213], v[64:67]
	v_mfma_f32_16x16x32_bf16 v[116:119], v[156:159], v[190:193], v[116:119]
	v_mfma_f32_16x16x32_bf16 v[112:115], v[182:185], v[190:193], v[112:115]
	v_mfma_f32_16x16x32_bf16 v[100:103], v[156:159], v[198:201], v[100:103]
	v_mfma_f32_16x16x32_bf16 v[96:99], v[182:185], v[198:201], v[96:99]
	v_mfma_f32_16x16x32_bf16 v[84:87], v[156:159], v[206:209], v[84:87]
	v_mfma_f32_16x16x32_bf16 v[80:83], v[182:185], v[206:209], v[80:83]
	v_mfma_f32_16x16x32_bf16 v[68:71], v[156:159], v[214:217], v[68:71]
	v_mfma_f32_16x16x32_bf16 v[64:67], v[182:185], v[214:217], v[64:67]
	s_barrier
	s_add_i32 s20, s96, s13
	v_lshl_add_u64 v[164:165], v[164:165], 0, s[6:7]
	s_mov_b32 m0, s20
	ds_read_b128 v[186:189], v171 offset:49152
	ds_read_b128 v[190:193], v171 offset:50176
	ds_read_b128 v[194:197], v171 offset:51200
	ds_read_b128 v[198:201], v171 offset:52224
	ds_read_b128 v[202:205], v171 offset:53248
	ds_read_b128 v[206:209], v171 offset:54272
	ds_read_b128 v[210:213], v171 offset:55296
	ds_read_b128 v[214:217], v171 offset:56320
	global_load_lds_dwordx4 v[164:165], off
	s_add_i32 m0, s20, 0x2000
	s_add_u32 s20, s24, 0x160080
	v_lshl_add_u64 v[164:165], v[174:175], 0, s[6:7]
	s_addc_u32 s21, s25, 0
	s_add_i32 s24, s97, s13
	global_load_lds_dwordx4 v[164:165], off
	s_mov_b32 m0, s24
	s_nop 0
	global_load_lds_dwordx4 v148, s[20:21]
	s_add_i32 m0, s24, 0x2000
	s_nop 0
	global_load_lds_dwordx4 v150, s[20:21]
	v_lshl_add_u64 v[164:165], v[218:219], 0, s[6:7]
	s_mov_b32 m0, s51
	s_nop 0
	global_load_lds_dwordx4 v[164:165], off
	v_lshl_add_u64 v[164:165], v[220:221], 0, s[6:7]
	s_mov_b32 m0, s52
	s_nop 0
	global_load_lds_dwordx4 v[164:165], off
	s_waitcnt vmcnt(8) lgkmcnt(0)
	s_barrier
	v_mfma_f32_16x16x32_bf16 v[60:63], v[124:127], v[186:189], v[60:63]
	v_mfma_f32_16x16x32_bf16 v[56:59], v[136:139], v[186:189], v[56:59]
	v_mfma_f32_16x16x32_bf16 v[44:47], v[124:127], v[194:197], v[44:47]
	v_mfma_f32_16x16x32_bf16 v[40:43], v[136:139], v[194:197], v[40:43]
	v_mfma_f32_16x16x32_bf16 v[28:31], v[124:127], v[202:205], v[28:31]
	v_mfma_f32_16x16x32_bf16 v[24:27], v[136:139], v[202:205], v[24:27]
	v_mfma_f32_16x16x32_bf16 v[12:15], v[124:127], v[210:213], v[12:15]
	v_mfma_f32_16x16x32_bf16 v[8:11], v[136:139], v[210:213], v[8:11]
	v_mfma_f32_16x16x32_bf16 v[60:63], v[132:135], v[190:193], v[60:63]
	v_mfma_f32_16x16x32_bf16 v[56:59], v[140:143], v[190:193], v[56:59]
	v_mfma_f32_16x16x32_bf16 v[44:47], v[132:135], v[198:201], v[44:47]
	v_mfma_f32_16x16x32_bf16 v[40:43], v[140:143], v[198:201], v[40:43]
	v_mfma_f32_16x16x32_bf16 v[28:31], v[132:135], v[206:209], v[28:31]
	v_mfma_f32_16x16x32_bf16 v[24:27], v[140:143], v[206:209], v[24:27]
	v_mfma_f32_16x16x32_bf16 v[12:15], v[132:135], v[214:217], v[12:15]
	v_mfma_f32_16x16x32_bf16 v[8:11], v[140:143], v[214:217], v[8:11]
	v_mfma_f32_16x16x32_bf16 v[52:55], v[144:147], v[186:189], v[52:55]
	v_mfma_f32_16x16x32_bf16 v[48:51], v[160:163], v[186:189], v[48:51]
	v_mfma_f32_16x16x32_bf16 v[36:39], v[144:147], v[194:197], v[36:39]
	v_mfma_f32_16x16x32_bf16 v[32:35], v[160:163], v[194:197], v[32:35]
	v_mfma_f32_16x16x32_bf16 v[20:23], v[144:147], v[202:205], v[20:23]
	v_mfma_f32_16x16x32_bf16 v[16:19], v[160:163], v[202:205], v[16:19]
	v_mfma_f32_16x16x32_bf16 v[4:7], v[144:147], v[210:213], v[4:7]
	v_mfma_f32_16x16x32_bf16 v[0:3], v[160:163], v[210:213], v[0:3]
	v_mfma_f32_16x16x32_bf16 v[52:55], v[156:159], v[190:193], v[52:55]
	v_mfma_f32_16x16x32_bf16 v[48:51], v[182:185], v[190:193], v[48:51]
	v_mfma_f32_16x16x32_bf16 v[36:39], v[156:159], v[198:201], v[36:39]
	v_mfma_f32_16x16x32_bf16 v[32:35], v[182:185], v[198:201], v[32:35]
	v_mfma_f32_16x16x32_bf16 v[20:23], v[156:159], v[206:209], v[20:23]
	v_mfma_f32_16x16x32_bf16 v[16:19], v[182:185], v[206:209], v[16:19]
	v_mfma_f32_16x16x32_bf16 v[4:7], v[156:159], v[214:217], v[4:7]
	v_mfma_f32_16x16x32_bf16 v[0:3], v[182:185], v[214:217], v[0:3]
	s_add_i32 s91, s91, 2
	s_add_u32 s89, s89, 0x100
	s_addc_u32 s90, s90, 0
	s_cmpk_gt_u32 s91, 0x55
	s_mov_b64 s[20:21], s[22:23]
	s_barrier
	s_cbranch_scc0 .LBB0_243
	s_setprio 0
	s_and_b64 vcc, exec, s[10:11]
	s_cbranch_vccz .LBB0_246
	s_barrier

; #define PG8_STAGE(bufoff, gbase, voff) do { _Pragma("unroll") for (int _i = 0; _i < 2; ++_i) \
;         __builtin_amdgcn_global_load_lds((const unsigned*)((const char*)(gbase) + (voff)[_i]), (LAS unsigned*)(lds + (bufoff) + ldsw + _i * 8192), 16, 0, 0); } while (0)
; #define PG8_LDA(dst, b, h) do { _Pragma("unroll") for (int m = 0; m < 4; ++m) _Pragma("unroll") for (int k = 0; k < 2; ++k) dst[m][k] = *(const LAS bf16x8*)(lds + PG8_SA(b, h) + aoff + m * 2048 + k * 1024); } while (0)
; #define PG8_LDB(dst, b, h) do { _Pragma("unroll") for (int n = 0; n < 2; ++n) _Pragma("unroll") for (int k = 0; k < 2; ++k) dst[n][k] = *(const LAS bf16x8*)(lds + PG8_SB(b, h) + boff + n * 2048 + k * 1024); } while (0)
; #define PG8_MMA(ai, bj, At, Bt) do { __builtin_amdgcn_s_setprio(1); _Pragma("unroll") for (int m = 0; m < 4; ++m) _Pragma("unroll") for (int n = 0; n < 2; ++n) _Pragma("unroll") for (int k = 0; k < 2; ++k) \
;         acc[ai][bj][m][n] = __builtin_amdgcn_mfma_f32_16x16x32_bf16(Bt[n][k], At[m][k], acc[ai][bj][m][n], 0, 0, 0); __builtin_amdgcn_s_setprio(0); } while (0)
; #define PG8_WAIT_V(n) asm volatile("s_waitcnt vmcnt(" #n ")" ::: "memory")
; #define PG8_WAIT_L(n) asm volatile("s_waitcnt lgkmcnt(" #n ")" ::: "memory")
; #define PG8_BAR __builtin_amdgcn_s_barrier()
; #define PG8_SCHED __builtin_amdgcn_sched_barrier(0)
; template <class Sched, class Epi, bool ALIGN_EPI, bool SP2>
; __device__ __forceinline__ void gemm_phase(LAS unsigned char* lds, const int K, const int lda, const int ldb, const Sched& S, const Epi& E) {
;     ...
;             PG8_LDB(B0, 0, 0); PG8_LDB(B1, 0, 1); PG8_SCHED; PG8_LDA(At, 0, 0); PG8_STAGE(PG8_SA(1, 1), a1 + hstepA, voffA);
;             PG8_WAIT_V(8); PG8_WAIT_L(0); PG8_BAR; PG8_MMA(0, 0, At, B0); PG8_MMA(0, 1, At, B1); PG8_BAR; PG8_SCHED;
;             PG8_LDA(At, 0, 1); PG8_STAGE(PG8_SB(0, 0), b2, voffB); PG8_STAGE(PG8_SB(0, 1), b2 + hstepB, voffB); PG8_STAGE(PG8_SA(0, 0), a2, voffA);
;             PG8_WAIT_V(8); PG8_WAIT_L(0); PG8_BAR; PG8_MMA(1, 0, At, B0); PG8_MMA(1, 1, At, B1); PG8_BAR; PG8_SCHED;
.LBB0_353:
	s_waitcnt lgkmcnt(0)
	ds_read_b128 v[32:35], v211
	ds_read_b128 v[36:39], v211 offset:1024
	ds_read_b128 v[48:51], v211 offset:2048
	ds_read_b128 v[52:55], v211 offset:3072
	ds_read_b128 v[56:59], v212
	ds_read_b128 v[60:63], v212 offset:1024
	ds_read_b128 v[64:67], v212 offset:2048
	ds_read_b128 v[68:71], v212 offset:3072
	s_add_u32 s8, s26, 0xfff80080
	s_addc_u32 s9, s27, -1
	s_cmp_eq_u32 s7, 28
	s_cselect_b32 s37, s1, s9
	s_cselect_b32 s36, s4, s8
	s_cselect_b32 s29, s21, s6
	s_cselect_b32 s28, vcc_lo, vcc_hi
	s_add_i32 m0, s89, 0xc000
	ds_read_b128 v[76:79], v213
	ds_read_b128 v[80:83], v213 offset:1024
	ds_read_b128 v[88:91], v213 offset:2048
	ds_read_b128 v[92:95], v213 offset:3072
	ds_read_b128 v[196:199], v213 offset:4096
	ds_read_b128 v[200:203], v213 offset:5120
	ds_read_b128 v[204:207], v213 offset:6144
	ds_read_b128 v[216:219], v213 offset:7168
	global_load_lds_dwordx4 v192, s[26:27]
	s_add_i32 m0, s89, 0xe000
	s_nop 0
	global_load_lds_dwordx4 v194, s[26:27]
	s_waitcnt vmcnt(8) lgkmcnt(0)
	s_barrier
	v_mfma_f32_16x16x32_bf16 v[172:175], v[32:35], v[76:79], v[172:175]
	v_mfma_f32_16x16x32_bf16 v[168:171], v[48:51], v[76:79], v[168:171]
	v_mfma_f32_16x16x32_bf16 v[156:159], v[32:35], v[88:91], v[156:159]
	v_mfma_f32_16x16x32_bf16 v[152:155], v[48:51], v[88:91], v[152:155]
	v_mfma_f32_16x16x32_bf16 v[140:143], v[32:35], v[196:199], v[140:143]
	v_mfma_f32_16x16x32_bf16 v[136:139], v[48:51], v[196:199], v[136:139]
	v_mfma_f32_16x16x32_bf16 v[124:127], v[32:35], v[204:207], v[124:127]
	v_mfma_f32_16x16x32_bf16 v[120:123], v[48:51], v[204:207], v[120:123]
	v_mfma_f32_16x16x32_bf16 v[172:175], v[36:39], v[80:83], v[172:175]
	v_mfma_f32_16x16x32_bf16 v[168:171], v[52:55], v[80:83], v[168:171]
	v_mfma_f32_16x16x32_bf16 v[156:159], v[36:39], v[92:95], v[156:159]
	v_mfma_f32_16x16x32_bf16 v[152:155], v[52:55], v[92:95], v[152:155]
	v_mfma_f32_16x16x32_bf16 v[140:143], v[36:39], v[200:203], v[140:143]
	v_mfma_f32_16x16x32_bf16 v[136:139], v[52:55], v[200:203], v[136:139]
	v_mfma_f32_16x16x32_bf16 v[124:127], v[36:39], v[216:219], v[124:127]
	v_mfma_f32_16x16x32_bf16 v[120:123], v[52:55], v[216:219], v[120:123]
	v_mfma_f32_16x16x32_bf16 v[164:167], v[56:59], v[76:79], v[164:167]
	v_mfma_f32_16x16x32_bf16 v[76:79], v[64:67], v[76:79], v[160:163]
	v_mfma_f32_16x16x32_bf16 v[164:167], v[60:63], v[80:83], v[164:167]
	v_mfma_f32_16x16x32_bf16 v[76:79], v[68:71], v[80:83], v[76:79]
	v_mfma_f32_16x16x32_bf16 v[80:83], v[56:59], v[88:91], v[148:151]
	v_mfma_f32_16x16x32_bf16 v[88:91], v[64:67], v[88:91], v[144:147]
	v_mfma_f32_16x16x32_bf16 v[128:131], v[64:67], v[196:199], v[128:131]
	v_mfma_f32_16x16x32_bf16 v[116:119], v[56:59], v[204:207], v[116:119]
	v_mfma_f32_16x16x32_bf16 v[112:115], v[64:67], v[204:207], v[112:115]
	v_mfma_f32_16x16x32_bf16 v[80:83], v[60:63], v[92:95], v[80:83]
	v_mfma_f32_16x16x32_bf16 v[88:91], v[68:71], v[92:95], v[88:91]
	v_mfma_f32_16x16x32_bf16 v[92:95], v[56:59], v[196:199], v[132:135]
	v_mfma_f32_16x16x32_bf16 v[128:131], v[68:71], v[200:203], v[128:131]
	v_mfma_f32_16x16x32_bf16 v[116:119], v[60:63], v[216:219], v[116:119]
	v_mfma_f32_16x16x32_bf16 v[112:115], v[68:71], v[216:219], v[112:115]
	v_mfma_f32_16x16x32_bf16 v[92:95], v[60:63], v[200:203], v[92:95]
	s_barrier
	s_add_i32 s8, s85, s88
	v_lshl_add_u64 v[208:209], s[28:29], 0, v[186:187]
	s_mov_b32 m0, s8
	ds_read_b128 v[132:135], v213 offset:16384
	ds_read_b128 v[144:147], v213 offset:17408
	ds_read_b128 v[148:151], v213 offset:18432
	ds_read_b128 v[160:163], v213 offset:19456
	ds_read_b128 v[196:199], v213 offset:20480
	ds_read_b128 v[200:203], v213 offset:21504
	ds_read_b128 v[204:207], v213 offset:22528
	ds_read_b128 v[216:219], v213 offset:23552
	global_load_lds_dwordx4 v[208:209], off
	s_add_i32 m0, s8, 0x2000
	s_add_u32 s8, s28, 0x80000
	v_lshl_add_u64 v[228:229], s[28:29], 0, v[190:191]
	s_addc_u32 s9, s29, 0
	s_add_i32 s51, s50, s88
	global_load_lds_dwordx4 v[228:229], off
	s_mov_b32 m0, s51
	v_lshl_add_u64 v[230:231], s[36:37], 0, v[184:185]
	global_load_lds_dwordx4 v186, s[8:9]
	s_add_i32 m0, s51, 0x2000
	v_lshl_add_u64 v[232:233], s[36:37], 0, v[188:189]
	global_load_lds_dwordx4 v190, s[8:9]
	s_mov_b32 m0, s89
	s_nop 0
	global_load_lds_dwordx4 v[230:231], off
	s_mov_b32 m0, s90
	s_nop 0
	global_load_lds_dwordx4 v[232:233], off
	s_waitcnt vmcnt(8) lgkmcnt(0)
	s_barrier
	v_mfma_f32_16x16x32_bf16 v[108:111], v[32:35], v[132:135], v[108:111]
	v_mfma_f32_16x16x32_bf16 v[104:107], v[48:51], v[132:135], v[104:107]
	v_mfma_f32_16x16x32_bf16 v[84:87], v[32:35], v[148:151], v[84:87]
	v_mfma_f32_16x16x32_bf16 v[72:75], v[48:51], v[148:151], v[72:75]
	v_mfma_f32_16x16x32_bf16 v[28:31], v[32:35], v[196:199], v[28:31]
	v_mfma_f32_16x16x32_bf16 v[24:27], v[48:51], v[196:199], v[24:27]
	v_mfma_f32_16x16x32_bf16 v[12:15], v[32:35], v[204:207], v[12:15]
	v_mfma_f32_16x16x32_bf16 v[8:11], v[48:51], v[204:207], v[8:11]
	v_mfma_f32_16x16x32_bf16 v[108:111], v[36:39], v[144:147], v[108:111]
	v_mfma_f32_16x16x32_bf16 v[104:107], v[52:55], v[144:147], v[104:107]
	v_mfma_f32_16x16x32_bf16 v[84:87], v[36:39], v[160:163], v[84:87]
	v_mfma_f32_16x16x32_bf16 v[72:75], v[52:55], v[160:163], v[72:75]
	v_mfma_f32_16x16x32_bf16 v[28:31], v[36:39], v[200:203], v[28:31]
	v_mfma_f32_16x16x32_bf16 v[24:27], v[52:55], v[200:203], v[24:27]
	v_mfma_f32_16x16x32_bf16 v[12:15], v[36:39], v[216:219], v[12:15]
	v_mfma_f32_16x16x32_bf16 v[8:11], v[52:55], v[216:219], v[8:11]
	v_mfma_f32_16x16x32_bf16 v[44:47], v[56:59], v[148:151], v[44:47]
	v_mfma_f32_16x16x32_bf16 v[40:43], v[64:67], v[148:151], v[40:43]
	v_mfma_f32_16x16x32_bf16 v[20:23], v[56:59], v[196:199], v[20:23]
	v_mfma_f32_16x16x32_bf16 v[16:19], v[64:67], v[196:199], v[16:19]
	v_mfma_f32_16x16x32_bf16 v[4:7], v[56:59], v[204:207], v[4:7]
	v_mfma_f32_16x16x32_bf16 v[0:3], v[64:67], v[204:207], v[0:3]
	v_mfma_f32_16x16x32_bf16 v[32:35], v[56:59], v[132:135], v[100:103]
	v_mfma_f32_16x16x32_bf16 v[36:39], v[64:67], v[132:135], v[96:99]
	v_mfma_f32_16x16x32_bf16 v[44:47], v[60:63], v[160:163], v[44:47]
	v_mfma_f32_16x16x32_bf16 v[40:43], v[68:71], v[160:163], v[40:43]
	v_mfma_f32_16x16x32_bf16 v[20:23], v[60:63], v[200:203], v[20:23]
	v_mfma_f32_16x16x32_bf16 v[16:19], v[68:71], v[200:203], v[16:19]
	v_mfma_f32_16x16x32_bf16 v[4:7], v[60:63], v[216:219], v[4:7]
	v_mfma_f32_16x16x32_bf16 v[0:3], v[68:71], v[216:219], v[0:3]
	v_mfma_f32_16x16x32_bf16 v[32:35], v[60:63], v[144:147], v[32:35]
	v_mfma_f32_16x16x32_bf16 v[36:39], v[68:71], v[144:147], v[36:39]
	s_barrier
; #define PG8_STAGE(bufoff, gbase, voff) do { _Pragma("unroll") for (int _i = 0; _i < 2; ++_i) \
;         __builtin_amdgcn_global_load_lds((const unsigned*)((const char*)(gbase) + (voff)[_i]), (LAS unsigned*)(lds + (bufoff) + ldsw + _i * 8192), 16, 0, 0); } while (0)
; #define PG8_LDA(dst, b, h) do { _Pragma("unroll") for (int m = 0; m < 4; ++m) _Pragma("unroll") for (int k = 0; k < 2; ++k) dst[m][k] = *(const LAS bf16x8*)(lds + PG8_SA(b, h) + aoff + m * 2048 + k * 1024); } while (0)
; #define PG8_LDB(dst, b, h) do { _Pragma("unroll") for (int n = 0; n < 2; ++n) _Pragma("unroll") for (int k = 0; k < 2; ++k) dst[n][k] = *(const LAS bf16x8*)(lds + PG8_SB(b, h) + boff + n * 2048 + k * 1024); } while (0)
; #define PG8_MMA(ai, bj, At, Bt) do { __builtin_amdgcn_s_setprio(1); _Pragma("unroll") for (int m = 0; m < 4; ++m) _Pragma("unroll") for (int n = 0; n < 2; ++n) _Pragma("unroll") for (int k = 0; k < 2; ++k) \
;         acc[ai][bj][m][n] = __builtin_amdgcn_mfma_f32_16x16x32_bf16(Bt[n][k], At[m][k], acc[ai][bj][m][n], 0, 0, 0); __builtin_amdgcn_s_setprio(0); } while (0)
; #define PG8_WAIT_V(n) asm volatile("s_waitcnt vmcnt(" #n ")" ::: "memory")
; #define PG8_WAIT_L(n) asm volatile("s_waitcnt lgkmcnt(" #n ")" ::: "memory")
; #define PG8_BAR __builtin_amdgcn_s_barrier()
; template <class Sched, class Epi, bool ALIGN_EPI, bool SP2>
; __device__ __forceinline__ void gemm_phase(LAS unsigned char* lds, const int K, const int lda, const int ldb, const Sched& S, const Epi& E) {
;     ...
;         for (int t = 0; t < nt; t += 2) {
;             const bool last = (t == nt - 2);
;             const char* a1 = cA + (size_t)(t + 1) * kstep;
;             const char* a2 = last ? nA : cA + (size_t)(t + 2) * kstep; const char* b2 = last ? nB : cB + (size_t)(t + 2) * kstep;
;             const char* a3 = a2 + kstep; const char* b3 = b2 + kstep;
;     ...
;             PG8_LDB(B0, 1, 0); PG8_LDB(B1, 1, 1); PG8_SCHED; PG8_LDA(At, 1, 0); PG8_STAGE(PG8_SA(0, 1), a2 + hstepA, voffA);
;             PG8_WAIT_V(8); PG8_WAIT_L(0); PG8_BAR; PG8_MMA(0, 0, At, B0); PG8_MMA(0, 1, At, B1); PG8_BAR; PG8_SCHED;
;             PG8_LDA(At, 1, 1); PG8_STAGE(PG8_SB(1, 0), b3, voffB); PG8_STAGE(PG8_SB(1, 1), b3 + hstepB, voffB); PG8_STAGE(PG8_SA(1, 0), a3, voffA);
;             PG8_WAIT_V(8); PG8_WAIT_L(0); PG8_BAR; PG8_MMA(1, 0, At, B0); PG8_MMA(1, 1, At, B1); PG8_BAR; PG8_SCHED;
	s_add_i32 s51, 0, 0x18000
	s_add_i32 s17, 0, 0x1c000
	v_add_u32_e32 v60, s51, v183
	v_add_u32_e32 v96, s17, v183
	ds_read_b128 v[48:51], v60
	ds_read_b128 v[52:55], v60 offset:1024
	ds_read_b128 v[56:59], v60 offset:2048
	ds_read_b128 v[60:63], v60 offset:3072
	ds_read_b128 v[64:67], v96
	ds_read_b128 v[68:71], v96 offset:1024
	ds_read_b128 v[196:199], v96 offset:2048
	ds_read_b128 v[200:203], v96 offset:3072
	s_add_u32 s8, s36, 0x80000
	s_addc_u32 s9, s37, 0
	s_mov_b32 m0, s91
	ds_read_b128 v[96:99], v213 offset:32768
	ds_read_b128 v[100:103], v213 offset:33792
	ds_read_b128 v[132:135], v213 offset:34816
	ds_read_b128 v[144:147], v213 offset:35840
	ds_read_b128 v[204:207], v213 offset:36864
	ds_read_b128 v[216:219], v213 offset:37888
	ds_read_b128 v[220:223], v213 offset:38912
	ds_read_b128 v[224:227], v213 offset:39936
	global_load_lds_dwordx4 v184, s[8:9]
	s_mov_b32 m0, s96
	s_nop 0
	global_load_lds_dwordx4 v188, s[8:9]
	s_waitcnt vmcnt(8) lgkmcnt(0)
	s_barrier
	v_mfma_f32_16x16x32_bf16 v[148:151], v[48:51], v[96:99], v[172:175]
	v_mfma_f32_16x16x32_bf16 v[172:175], v[52:55], v[100:103], v[148:151]
	v_mfma_f32_16x16x32_bf16 v[148:151], v[56:59], v[96:99], v[168:171]
	v_mfma_f32_16x16x32_bf16 v[168:171], v[60:63], v[100:103], v[148:151]
	v_mfma_f32_16x16x32_bf16 v[148:151], v[48:51], v[132:135], v[156:159]
	v_mfma_f32_16x16x32_bf16 v[156:159], v[52:55], v[144:147], v[148:151]
	v_mfma_f32_16x16x32_bf16 v[148:151], v[56:59], v[132:135], v[152:155]
	v_mfma_f32_16x16x32_bf16 v[140:143], v[48:51], v[204:207], v[140:143]
	v_mfma_f32_16x16x32_bf16 v[136:139], v[56:59], v[204:207], v[136:139]
	v_mfma_f32_16x16x32_bf16 v[124:127], v[48:51], v[220:223], v[124:127]
	v_mfma_f32_16x16x32_bf16 v[120:123], v[56:59], v[220:223], v[120:123]
	v_mfma_f32_16x16x32_bf16 v[152:155], v[60:63], v[144:147], v[148:151]
	v_mfma_f32_16x16x32_bf16 v[140:143], v[52:55], v[216:219], v[140:143]
	v_mfma_f32_16x16x32_bf16 v[136:139], v[60:63], v[216:219], v[136:139]
	v_mfma_f32_16x16x32_bf16 v[124:127], v[52:55], v[224:227], v[124:127]
	v_mfma_f32_16x16x32_bf16 v[120:123], v[60:63], v[224:227], v[120:123]
	v_mfma_f32_16x16x32_bf16 v[76:79], v[196:199], v[96:99], v[76:79]
	v_mfma_f32_16x16x32_bf16 v[148:151], v[64:67], v[96:99], v[164:167]
	v_mfma_f32_16x16x32_bf16 v[160:163], v[200:203], v[100:103], v[76:79]
	v_mfma_f32_16x16x32_bf16 v[76:79], v[64:67], v[132:135], v[80:83]
	v_mfma_f32_16x16x32_bf16 v[164:167], v[68:71], v[100:103], v[148:151]
	v_mfma_f32_16x16x32_bf16 v[148:151], v[68:71], v[144:147], v[76:79]
	v_mfma_f32_16x16x32_bf16 v[76:79], v[196:199], v[132:135], v[88:91]
	v_mfma_f32_16x16x32_bf16 v[144:147], v[200:203], v[144:147], v[76:79]
	v_mfma_f32_16x16x32_bf16 v[76:79], v[64:67], v[204:207], v[92:95]
	v_mfma_f32_16x16x32_bf16 v[132:135], v[68:71], v[216:219], v[76:79]
	v_mfma_f32_16x16x32_bf16 v[76:79], v[196:199], v[204:207], v[128:131]
	v_mfma_f32_16x16x32_bf16 v[128:131], v[200:203], v[216:219], v[76:79]
	v_mfma_f32_16x16x32_bf16 v[76:79], v[64:67], v[220:223], v[116:119]
	v_mfma_f32_16x16x32_bf16 v[116:119], v[68:71], v[224:227], v[76:79]
	v_mfma_f32_16x16x32_bf16 v[76:79], v[196:199], v[220:223], v[112:115]
	v_mfma_f32_16x16x32_bf16 v[112:115], v[200:203], v[224:227], v[76:79]
	s_barrier
	s_add_i32 s8, s51, s88
	v_lshl_add_u64 v[96:97], v[208:209], 0, s[10:11]
	s_mov_b32 m0, s8
	s_nop 1
	ds_read_b128 v[76:79], v213 offset:49152
	ds_read_b128 v[80:83], v213 offset:50176
	ds_read_b128 v[88:91], v213 offset:51200
	ds_read_b128 v[92:95], v213 offset:52224
	ds_read_b128 v[204:207], v213 offset:53248
	ds_read_b128 v[216:219], v213 offset:54272
	ds_read_b128 v[220:223], v213 offset:55296
	ds_read_b128 v[224:227], v213 offset:56320
	global_load_lds_dwordx4 v[96:97], off
	s_add_i32 m0, s8, 0x2000
	s_add_u32 s8, s28, 0x80080
	v_lshl_add_u64 v[96:97], v[228:229], 0, s[10:11]
	s_addc_u32 s9, s29, 0
	s_add_i32 s17, s17, s88
	global_load_lds_dwordx4 v[96:97], off
	s_mov_b32 m0, s17
	s_nop 0
	global_load_lds_dwordx4 v186, s[8:9]
	s_add_i32 m0, s17, 0x2000
	s_nop 0
	global_load_lds_dwordx4 v190, s[8:9]
	v_lshl_add_u64 v[96:97], v[230:231], 0, s[10:11]
	s_mov_b32 m0, s97
	s_nop 0
	global_load_lds_dwordx4 v[96:97], off
	v_lshl_add_u64 v[96:97], v[232:233], 0, s[10:11]
	s_mov_b32 m0, s84
	s_nop 0
	global_load_lds_dwordx4 v[96:97], off
	s_waitcnt vmcnt(8) lgkmcnt(0)
	s_barrier
	v_mfma_f32_16x16x32_bf16 v[96:99], v[48:51], v[76:79], v[108:111]
	v_mfma_f32_16x16x32_bf16 v[108:111], v[52:55], v[80:83], v[96:99]
	v_mfma_f32_16x16x32_bf16 v[96:99], v[56:59], v[76:79], v[104:107]
	v_mfma_f32_16x16x32_bf16 v[84:87], v[48:51], v[88:91], v[84:87]
	v_mfma_f32_16x16x32_bf16 v[72:75], v[56:59], v[88:91], v[72:75]
	v_mfma_f32_16x16x32_bf16 v[28:31], v[48:51], v[204:207], v[28:31]
	v_mfma_f32_16x16x32_bf16 v[24:27], v[56:59], v[204:207], v[24:27]
	v_mfma_f32_16x16x32_bf16 v[12:15], v[48:51], v[220:223], v[12:15]
	v_mfma_f32_16x16x32_bf16 v[8:11], v[56:59], v[220:223], v[8:11]
	v_mfma_f32_16x16x32_bf16 v[104:107], v[60:63], v[80:83], v[96:99]
	v_mfma_f32_16x16x32_bf16 v[84:87], v[52:55], v[92:95], v[84:87]
	v_mfma_f32_16x16x32_bf16 v[72:75], v[60:63], v[92:95], v[72:75]
	v_mfma_f32_16x16x32_bf16 v[28:31], v[52:55], v[216:219], v[28:31]
	v_mfma_f32_16x16x32_bf16 v[24:27], v[60:63], v[216:219], v[24:27]
	v_mfma_f32_16x16x32_bf16 v[12:15], v[52:55], v[224:227], v[12:15]
	v_mfma_f32_16x16x32_bf16 v[8:11], v[60:63], v[224:227], v[8:11]
	v_mfma_f32_16x16x32_bf16 v[32:35], v[64:67], v[76:79], v[32:35]
	v_mfma_f32_16x16x32_bf16 v[100:103], v[68:71], v[80:83], v[32:35]
	v_mfma_f32_16x16x32_bf16 v[32:35], v[196:199], v[76:79], v[36:39]
	v_mfma_f32_16x16x32_bf16 v[96:99], v[200:203], v[80:83], v[32:35]
	v_mfma_f32_16x16x32_bf16 v[32:35], v[64:67], v[88:91], v[44:47]
	v_mfma_f32_16x16x32_bf16 v[44:47], v[68:71], v[92:95], v[32:35]
	v_mfma_f32_16x16x32_bf16 v[32:35], v[196:199], v[88:91], v[40:43]
	v_mfma_f32_16x16x32_bf16 v[20:23], v[64:67], v[204:207], v[20:23]
	v_mfma_f32_16x16x32_bf16 v[16:19], v[196:199], v[204:207], v[16:19]
	v_mfma_f32_16x16x32_bf16 v[4:7], v[64:67], v[220:223], v[4:7]
	v_mfma_f32_16x16x32_bf16 v[0:3], v[196:199], v[220:223], v[0:3]
	v_mfma_f32_16x16x32_bf16 v[40:43], v[200:203], v[92:95], v[32:35]
	v_mfma_f32_16x16x32_bf16 v[20:23], v[68:71], v[216:219], v[20:23]
	v_mfma_f32_16x16x32_bf16 v[16:19], v[200:203], v[216:219], v[16:19]
	v_mfma_f32_16x16x32_bf16 v[4:7], v[68:71], v[224:227], v[4:7]
	v_mfma_f32_16x16x32_bf16 v[0:3], v[200:203], v[224:227], v[0:3]
	s_add_i32 s7, s7, 2
	s_add_u32 s26, s26, 0x100
	s_addc_u32 s27, s27, 0
	s_add_u32 vcc_hi, vcc_hi, 0x100
	s_addc_u32 s6, s6, 0
	s_cmp_gt_u32 s7, 29
	s_barrier
	s_cbranch_scc0 .LBB0_353
	s_setprio 0
	s_and_b64 vcc, exec, s[12:13]
	s_cbranch_vccz .LBB0_356
	s_barrier

; #define PG8_STAGE(bufoff, gbase, voff) do { _Pragma("unroll") for (int _i = 0; _i < 2; ++_i) \
;         __builtin_amdgcn_global_load_lds((const unsigned*)((const char*)(gbase) + (voff)[_i]), (LAS unsigned*)(lds + (bufoff) + ldsw + _i * 8192), 16, 0, 0); } while (0)
; #define PG8_LDA(dst, b, h) do { _Pragma("unroll") for (int m = 0; m < 4; ++m) _Pragma("unroll") for (int k = 0; k < 2; ++k) dst[m][k] = *(const LAS bf16x8*)(lds + PG8_SA(b, h) + aoff + m * 2048 + k * 1024); } while (0)
; #define PG8_LDB(dst, b, h) do { _Pragma("unroll") for (int n = 0; n < 2; ++n) _Pragma("unroll") for (int k = 0; k < 2; ++k) dst[n][k] = *(const LAS bf16x8*)(lds + PG8_SB(b, h) + boff + n * 2048 + k * 1024); } while (0)
; #define PG8_MMA(ai, bj, At, Bt) do { __builtin_amdgcn_s_setprio(1); _Pragma("unroll") for (int m = 0; m < 4; ++m) _Pragma("unroll") for (int n = 0; n < 2; ++n) _Pragma("unroll") for (int k = 0; k < 2; ++k) \
;         acc[ai][bj][m][n] = __builtin_amdgcn_mfma_f32_16x16x32_bf16(Bt[n][k], At[m][k], acc[ai][bj][m][n], 0, 0, 0); __builtin_amdgcn_s_setprio(0); } while (0)
; #define PG8_WAIT_V(n) asm volatile("s_waitcnt vmcnt(" #n ")" ::: "memory")
; #define PG8_WAIT_L(n) asm volatile("s_waitcnt lgkmcnt(" #n ")" ::: "memory")
; #define PG8_BAR __builtin_amdgcn_s_barrier()
; #define PG8_SCHED __builtin_amdgcn_sched_barrier(0)
; template <class Sched, class Epi, bool ALIGN_EPI, bool SP2>
; __device__ __forceinline__ void gemm_phase(LAS unsigned char* lds, const int K, const int lda, const int ldb, const Sched& S, const Epi& E) {
;     ...
;             PG8_LDB(B0, 0, 0); PG8_LDB(B1, 0, 1); PG8_SCHED; PG8_LDA(At, 0, 0); PG8_STAGE(PG8_SA(1, 1), a1 + hstepA, voffA);
;             PG8_WAIT_V(8); PG8_WAIT_L(0); PG8_BAR; PG8_MMA(0, 0, At, B0); PG8_MMA(0, 1, At, B1); PG8_BAR; PG8_SCHED;
;             PG8_LDA(At, 0, 1); PG8_STAGE(PG8_SB(0, 0), b2, voffB); PG8_STAGE(PG8_SB(0, 1), b2 + hstepB, voffB); PG8_STAGE(PG8_SA(0, 0), a2, voffA);
;             PG8_WAIT_V(8); PG8_WAIT_L(0); PG8_BAR; PG8_MMA(1, 0, At, B0); PG8_MMA(1, 1, At, B1); PG8_BAR; PG8_SCHED;
.LBB0_945:
	ds_read_b128 v[52:55], v209
	ds_read_b128 v[56:59], v209 offset:1024
	ds_read_b128 v[64:67], v209 offset:2048
	ds_read_b128 v[68:71], v209 offset:3072
	ds_read_b128 v[72:75], v210
	ds_read_b128 v[76:79], v210 offset:1024
	ds_read_b128 v[88:91], v210 offset:2048
	ds_read_b128 v[92:95], v210 offset:3072
	s_add_u32 s42, s36, 0xfff80080
	s_addc_u32 s43, s37, -1
	s_cmp_eq_u32 s61, 28
	s_cselect_b32 s45, s27, s43
	s_cselect_b32 s44, s26, s42
	s_cselect_b32 s43, s29, s25
	s_cselect_b32 s42, s28, s1
	s_add_i32 m0, s21, 0xc000
	ds_read_b128 v[160:163], v211
	ds_read_b128 v[164:167], v211 offset:1024
	ds_read_b128 v[168:171], v211 offset:2048
	ds_read_b128 v[172:175], v211 offset:3072
	ds_read_b128 v[190:193], v211 offset:4096
	ds_read_b128 v[194:197], v211 offset:5120
	ds_read_b128 v[198:201], v211 offset:6144
	ds_read_b128 v[202:205], v211 offset:7168
	global_load_lds_dwordx4 v186, s[36:37]
	s_add_i32 m0, s21, 0xe000
	s_nop 0
	global_load_lds_dwordx4 v188, s[36:37]
	s_waitcnt vmcnt(8) lgkmcnt(0)
	s_barrier
	v_mfma_f32_16x16x32_bf16 v[156:159], v[52:55], v[160:163], v[156:159]
	v_mfma_f32_16x16x32_bf16 v[152:155], v[64:67], v[160:163], v[152:155]
	v_mfma_f32_16x16x32_bf16 v[140:143], v[52:55], v[168:171], v[140:143]
	v_mfma_f32_16x16x32_bf16 v[136:139], v[64:67], v[168:171], v[136:139]
	v_mfma_f32_16x16x32_bf16 v[124:127], v[52:55], v[190:193], v[124:127]
	v_mfma_f32_16x16x32_bf16 v[120:123], v[64:67], v[190:193], v[120:123]
	v_mfma_f32_16x16x32_bf16 v[108:111], v[52:55], v[198:201], v[108:111]
	v_mfma_f32_16x16x32_bf16 v[104:107], v[64:67], v[198:201], v[104:107]
	v_mfma_f32_16x16x32_bf16 v[156:159], v[56:59], v[164:167], v[156:159]
	v_mfma_f32_16x16x32_bf16 v[152:155], v[68:71], v[164:167], v[152:155]
	v_mfma_f32_16x16x32_bf16 v[140:143], v[56:59], v[172:175], v[140:143]
	v_mfma_f32_16x16x32_bf16 v[136:139], v[68:71], v[172:175], v[136:139]
	v_mfma_f32_16x16x32_bf16 v[124:127], v[56:59], v[194:197], v[124:127]
	v_mfma_f32_16x16x32_bf16 v[120:123], v[68:71], v[194:197], v[120:123]
	v_mfma_f32_16x16x32_bf16 v[108:111], v[56:59], v[202:205], v[108:111]
	v_mfma_f32_16x16x32_bf16 v[104:107], v[68:71], v[202:205], v[104:107]
	v_mfma_f32_16x16x32_bf16 v[148:151], v[72:75], v[160:163], v[148:151]
	v_mfma_f32_16x16x32_bf16 v[144:147], v[88:91], v[160:163], v[144:147]
	v_mfma_f32_16x16x32_bf16 v[132:135], v[72:75], v[168:171], v[132:135]
	v_mfma_f32_16x16x32_bf16 v[128:131], v[88:91], v[168:171], v[128:131]
	v_mfma_f32_16x16x32_bf16 v[116:119], v[72:75], v[190:193], v[116:119]
	v_mfma_f32_16x16x32_bf16 v[112:115], v[88:91], v[190:193], v[112:115]
	v_mfma_f32_16x16x32_bf16 v[100:103], v[72:75], v[198:201], v[100:103]
	v_mfma_f32_16x16x32_bf16 v[96:99], v[88:91], v[198:201], v[96:99]
	v_mfma_f32_16x16x32_bf16 v[148:151], v[76:79], v[164:167], v[148:151]
	v_mfma_f32_16x16x32_bf16 v[144:147], v[92:95], v[164:167], v[144:147]
	v_mfma_f32_16x16x32_bf16 v[132:135], v[76:79], v[172:175], v[132:135]
	v_mfma_f32_16x16x32_bf16 v[128:131], v[92:95], v[172:175], v[128:131]
	v_mfma_f32_16x16x32_bf16 v[116:119], v[76:79], v[194:197], v[116:119]
	v_mfma_f32_16x16x32_bf16 v[112:115], v[92:95], v[194:197], v[112:115]
	v_mfma_f32_16x16x32_bf16 v[100:103], v[76:79], v[202:205], v[100:103]
	v_mfma_f32_16x16x32_bf16 v[96:99], v[92:95], v[202:205], v[96:99]
	s_barrier
	s_add_i32 s62, s50, s19
	v_lshl_add_u64 v[206:207], s[42:43], 0, v[182:183]
	s_mov_b32 m0, s62
	ds_read_b128 v[160:163], v211 offset:16384
	ds_read_b128 v[164:167], v211 offset:17408
	ds_read_b128 v[168:171], v211 offset:18432
	ds_read_b128 v[172:175], v211 offset:19456
	ds_read_b128 v[190:193], v211 offset:20480
	ds_read_b128 v[194:197], v211 offset:21504
	ds_read_b128 v[198:201], v211 offset:22528
	ds_read_b128 v[202:205], v211 offset:23552
	global_load_lds_dwordx4 v[206:207], off
	s_add_i32 m0, s62, 0x2000
	s_add_u32 s62, s42, 0x80000
	v_lshl_add_u64 v[214:215], s[42:43], 0, v[184:185]
	s_addc_u32 s63, s43, 0
	s_add_i32 s64, s51, s19
	global_load_lds_dwordx4 v[214:215], off
	s_mov_b32 m0, s64
	v_lshl_add_u64 v[218:219], s[44:45], 0, v[184:185]
	global_load_lds_dwordx4 v182, s[62:63]
	s_add_i32 m0, s64, 0x2000
	s_nop 0
	global_load_lds_dwordx4 v184, s[62:63]
	v_lshl_add_u64 v[216:217], s[44:45], 0, v[182:183]
	s_mov_b32 m0, s21
	s_nop 0
	global_load_lds_dwordx4 v[216:217], off
	s_mov_b32 m0, s33
	s_nop 0
	global_load_lds_dwordx4 v[218:219], off
	s_waitcnt vmcnt(8) lgkmcnt(0)
	s_barrier
	v_mfma_f32_16x16x32_bf16 v[84:87], v[52:55], v[160:163], v[84:87]
	v_mfma_f32_16x16x32_bf16 v[80:83], v[64:67], v[160:163], v[80:83]
	v_mfma_f32_16x16x32_bf16 v[44:47], v[52:55], v[168:171], v[44:47]
	v_mfma_f32_16x16x32_bf16 v[40:43], v[64:67], v[168:171], v[40:43]
	v_mfma_f32_16x16x32_bf16 v[28:31], v[52:55], v[190:193], v[28:31]
	v_mfma_f32_16x16x32_bf16 v[24:27], v[64:67], v[190:193], v[24:27]
	v_mfma_f32_16x16x32_bf16 v[12:15], v[52:55], v[198:201], v[12:15]
	v_mfma_f32_16x16x32_bf16 v[8:11], v[64:67], v[198:201], v[8:11]
	v_mfma_f32_16x16x32_bf16 v[84:87], v[56:59], v[164:167], v[84:87]
	v_mfma_f32_16x16x32_bf16 v[80:83], v[68:71], v[164:167], v[80:83]
	v_mfma_f32_16x16x32_bf16 v[44:47], v[56:59], v[172:175], v[44:47]
	v_mfma_f32_16x16x32_bf16 v[40:43], v[68:71], v[172:175], v[40:43]
	v_mfma_f32_16x16x32_bf16 v[28:31], v[56:59], v[194:197], v[28:31]
	v_mfma_f32_16x16x32_bf16 v[24:27], v[68:71], v[194:197], v[24:27]
	v_mfma_f32_16x16x32_bf16 v[12:15], v[56:59], v[202:205], v[12:15]
	v_mfma_f32_16x16x32_bf16 v[8:11], v[68:71], v[202:205], v[8:11]
	v_mfma_f32_16x16x32_bf16 v[48:51], v[88:91], v[160:163], v[48:51]
	v_mfma_f32_16x16x32_bf16 v[36:39], v[72:75], v[168:171], v[36:39]
	v_mfma_f32_16x16x32_bf16 v[32:35], v[88:91], v[168:171], v[32:35]
	v_mfma_f32_16x16x32_bf16 v[20:23], v[72:75], v[190:193], v[20:23]
	v_mfma_f32_16x16x32_bf16 v[16:19], v[88:91], v[190:193], v[16:19]
	v_mfma_f32_16x16x32_bf16 v[4:7], v[72:75], v[198:201], v[4:7]
	v_mfma_f32_16x16x32_bf16 v[0:3], v[88:91], v[198:201], v[0:3]
	v_mfma_f32_16x16x32_bf16 v[52:55], v[72:75], v[160:163], v[60:63]
	v_mfma_f32_16x16x32_bf16 v[48:51], v[92:95], v[164:167], v[48:51]
	v_mfma_f32_16x16x32_bf16 v[36:39], v[76:79], v[172:175], v[36:39]
	v_mfma_f32_16x16x32_bf16 v[32:35], v[92:95], v[172:175], v[32:35]
	v_mfma_f32_16x16x32_bf16 v[20:23], v[76:79], v[194:197], v[20:23]
	v_mfma_f32_16x16x32_bf16 v[16:19], v[92:95], v[194:197], v[16:19]
	v_mfma_f32_16x16x32_bf16 v[4:7], v[76:79], v[202:205], v[4:7]
	v_mfma_f32_16x16x32_bf16 v[0:3], v[92:95], v[202:205], v[0:3]
	v_mfma_f32_16x16x32_bf16 v[52:55], v[76:79], v[164:167], v[52:55]
	s_barrier
; #define PG8_STAGE(bufoff, gbase, voff) do { _Pragma("unroll") for (int _i = 0; _i < 2; ++_i) \
;         __builtin_amdgcn_global_load_lds((const unsigned*)((const char*)(gbase) + (voff)[_i]), (LAS unsigned*)(lds + (bufoff) + ldsw + _i * 8192), 16, 0, 0); } while (0)
; #define PG8_LDA(dst, b, h) do { _Pragma("unroll") for (int m = 0; m < 4; ++m) _Pragma("unroll") for (int k = 0; k < 2; ++k) dst[m][k] = *(const LAS bf16x8*)(lds + PG8_SA(b, h) + aoff + m * 2048 + k * 1024); } while (0)
; #define PG8_LDB(dst, b, h) do { _Pragma("unroll") for (int n = 0; n < 2; ++n) _Pragma("unroll") for (int k = 0; k < 2; ++k) dst[n][k] = *(const LAS bf16x8*)(lds + PG8_SB(b, h) + boff + n * 2048 + k * 1024); } while (0)
; #define PG8_MMA(ai, bj, At, Bt) do { __builtin_amdgcn_s_setprio(1); _Pragma("unroll") for (int m = 0; m < 4; ++m) _Pragma("unroll") for (int n = 0; n < 2; ++n) _Pragma("unroll") for (int k = 0; k < 2; ++k) \
;         acc[ai][bj][m][n] = __builtin_amdgcn_mfma_f32_16x16x32_bf16(Bt[n][k], At[m][k], acc[ai][bj][m][n], 0, 0, 0); __builtin_amdgcn_s_setprio(0); } while (0)
; #define PG8_WAIT_V(n) asm volatile("s_waitcnt vmcnt(" #n ")" ::: "memory")
; #define PG8_WAIT_L(n) asm volatile("s_waitcnt lgkmcnt(" #n ")" ::: "memory")
; #define PG8_BAR __builtin_amdgcn_s_barrier()
; template <class Sched, class Epi, bool ALIGN_EPI, bool SP2>
; __device__ __forceinline__ void gemm_phase(LAS unsigned char* lds, const int K, const int lda, const int ldb, const Sched& S, const Epi& E) {
;     ...
;         for (int t = 0; t < nt; t += 2) {
;             const bool last = (t == nt - 2);
;             const char* a1 = cA + (size_t)(t + 1) * kstep;
;             const char* a2 = last ? nA : cA + (size_t)(t + 2) * kstep; const char* b2 = last ? nB : cB + (size_t)(t + 2) * kstep;
;             const char* a3 = a2 + kstep; const char* b3 = b2 + kstep;
;     ...
;             PG8_LDB(B0, 1, 0); PG8_LDB(B1, 1, 1); PG8_SCHED; PG8_LDA(At, 1, 0); PG8_STAGE(PG8_SA(0, 1), a2 + hstepA, voffA);
;             PG8_WAIT_V(8); PG8_WAIT_L(0); PG8_BAR; PG8_MMA(0, 0, At, B0); PG8_MMA(0, 1, At, B1); PG8_BAR; PG8_SCHED;
;             PG8_LDA(At, 1, 1); PG8_STAGE(PG8_SB(1, 0), b3, voffB); PG8_STAGE(PG8_SB(1, 1), b3 + hstepB, voffB); PG8_STAGE(PG8_SA(1, 0), a3, voffA);
;             PG8_WAIT_V(8); PG8_WAIT_L(0); PG8_BAR; PG8_MMA(1, 0, At, B0); PG8_MMA(1, 1, At, B1); PG8_BAR; PG8_SCHED;
	s_add_i32 s62, 0, 0x18000
	s_add_i32 s63, 0, 0x1c000
	v_add_u32_e32 v68, s62, v181
	v_add_u32_e32 v92, s63, v181
	ds_read_b128 v[56:59], v68
	ds_read_b128 v[60:63], v68 offset:1024
	ds_read_b128 v[64:67], v68 offset:2048
	ds_read_b128 v[68:71], v68 offset:3072
	ds_read_b128 v[72:75], v92
	ds_read_b128 v[76:79], v92 offset:1024
	ds_read_b128 v[88:91], v92 offset:2048
	ds_read_b128 v[92:95], v92 offset:3072
	s_add_u32 s44, s44, 0x80000
	s_addc_u32 s45, s45, 0
	s_mov_b32 m0, s35
	ds_read_b128 v[160:163], v211 offset:32768
	ds_read_b128 v[164:167], v211 offset:33792
	ds_read_b128 v[168:171], v211 offset:34816
	ds_read_b128 v[172:175], v211 offset:35840
	ds_read_b128 v[190:193], v211 offset:36864
	ds_read_b128 v[194:197], v211 offset:37888
	ds_read_b128 v[198:201], v211 offset:38912
	ds_read_b128 v[202:205], v211 offset:39936
	global_load_lds_dwordx4 v182, s[44:45]
	s_mov_b32 m0, s46
	s_nop 0
	global_load_lds_dwordx4 v184, s[44:45]
	s_waitcnt vmcnt(8) lgkmcnt(0)
	s_barrier
	v_mfma_f32_16x16x32_bf16 v[156:159], v[56:59], v[160:163], v[156:159]
	v_mfma_f32_16x16x32_bf16 v[152:155], v[64:67], v[160:163], v[152:155]
	v_mfma_f32_16x16x32_bf16 v[140:143], v[56:59], v[168:171], v[140:143]
	v_mfma_f32_16x16x32_bf16 v[136:139], v[64:67], v[168:171], v[136:139]
	v_mfma_f32_16x16x32_bf16 v[124:127], v[56:59], v[190:193], v[124:127]
	v_mfma_f32_16x16x32_bf16 v[120:123], v[64:67], v[190:193], v[120:123]
	v_mfma_f32_16x16x32_bf16 v[108:111], v[56:59], v[198:201], v[108:111]
	v_mfma_f32_16x16x32_bf16 v[104:107], v[64:67], v[198:201], v[104:107]
	v_mfma_f32_16x16x32_bf16 v[156:159], v[60:63], v[164:167], v[156:159]
	v_mfma_f32_16x16x32_bf16 v[152:155], v[68:71], v[164:167], v[152:155]
	v_mfma_f32_16x16x32_bf16 v[140:143], v[60:63], v[172:175], v[140:143]
	v_mfma_f32_16x16x32_bf16 v[136:139], v[68:71], v[172:175], v[136:139]
	v_mfma_f32_16x16x32_bf16 v[124:127], v[60:63], v[194:197], v[124:127]
	v_mfma_f32_16x16x32_bf16 v[120:123], v[68:71], v[194:197], v[120:123]
	v_mfma_f32_16x16x32_bf16 v[108:111], v[60:63], v[202:205], v[108:111]
	v_mfma_f32_16x16x32_bf16 v[104:107], v[68:71], v[202:205], v[104:107]
	v_mfma_f32_16x16x32_bf16 v[148:151], v[72:75], v[160:163], v[148:151]
	v_mfma_f32_16x16x32_bf16 v[144:147], v[88:91], v[160:163], v[144:147]
	v_mfma_f32_16x16x32_bf16 v[132:135], v[72:75], v[168:171], v[132:135]
	v_mfma_f32_16x16x32_bf16 v[128:131], v[88:91], v[168:171], v[128:131]
	v_mfma_f32_16x16x32_bf16 v[116:119], v[72:75], v[190:193], v[116:119]
	v_mfma_f32_16x16x32_bf16 v[112:115], v[88:91], v[190:193], v[112:115]
	v_mfma_f32_16x16x32_bf16 v[100:103], v[72:75], v[198:201], v[100:103]
	v_mfma_f32_16x16x32_bf16 v[96:99], v[88:91], v[198:201], v[96:99]
	v_mfma_f32_16x16x32_bf16 v[148:151], v[76:79], v[164:167], v[148:151]
	v_mfma_f32_16x16x32_bf16 v[144:147], v[92:95], v[164:167], v[144:147]
	v_mfma_f32_16x16x32_bf16 v[132:135], v[76:79], v[172:175], v[132:135]
	v_mfma_f32_16x16x32_bf16 v[128:131], v[92:95], v[172:175], v[128:131]
	v_mfma_f32_16x16x32_bf16 v[116:119], v[76:79], v[194:197], v[116:119]
	v_mfma_f32_16x16x32_bf16 v[112:115], v[92:95], v[194:197], v[112:115]
	v_mfma_f32_16x16x32_bf16 v[100:103], v[76:79], v[202:205], v[100:103]
	v_mfma_f32_16x16x32_bf16 v[96:99], v[92:95], v[202:205], v[96:99]
	s_barrier
	s_add_i32 s44, s62, s19
	v_lshl_add_u64 v[206:207], v[206:207], 0, s[14:15]
	s_mov_b32 m0, s44
	ds_read_b128 v[160:163], v211 offset:49152
	ds_read_b128 v[164:167], v211 offset:50176
	ds_read_b128 v[168:171], v211 offset:51200
	ds_read_b128 v[172:175], v211 offset:52224
	ds_read_b128 v[190:193], v211 offset:53248
	ds_read_b128 v[194:197], v211 offset:54272
	ds_read_b128 v[198:201], v211 offset:55296
	ds_read_b128 v[202:205], v211 offset:56320
	global_load_lds_dwordx4 v[206:207], off
	s_add_i32 m0, s44, 0x2000
	s_add_u32 s42, s42, 0x80080
	v_lshl_add_u64 v[206:207], v[214:215], 0, s[14:15]
	s_addc_u32 s43, s43, 0
	s_add_i32 s44, s63, s19
	global_load_lds_dwordx4 v[206:207], off
	s_mov_b32 m0, s44
	s_nop 0
	global_load_lds_dwordx4 v182, s[42:43]
	s_add_i32 m0, s44, 0x2000
	s_nop 0
	global_load_lds_dwordx4 v184, s[42:43]
	v_lshl_add_u64 v[206:207], v[216:217], 0, s[14:15]
	s_mov_b32 m0, s48
	s_nop 0
	global_load_lds_dwordx4 v[206:207], off
	v_lshl_add_u64 v[206:207], v[218:219], 0, s[14:15]
	s_mov_b32 m0, s49
	s_nop 0
	global_load_lds_dwordx4 v[206:207], off
	s_waitcnt vmcnt(8) lgkmcnt(0)
	s_barrier
	v_mfma_f32_16x16x32_bf16 v[84:87], v[56:59], v[160:163], v[84:87]
	v_mfma_f32_16x16x32_bf16 v[80:83], v[64:67], v[160:163], v[80:83]
	v_mfma_f32_16x16x32_bf16 v[44:47], v[56:59], v[168:171], v[44:47]
	v_mfma_f32_16x16x32_bf16 v[40:43], v[64:67], v[168:171], v[40:43]
	v_mfma_f32_16x16x32_bf16 v[28:31], v[56:59], v[190:193], v[28:31]
	v_mfma_f32_16x16x32_bf16 v[24:27], v[64:67], v[190:193], v[24:27]
	v_mfma_f32_16x16x32_bf16 v[12:15], v[56:59], v[198:201], v[12:15]
	v_mfma_f32_16x16x32_bf16 v[8:11], v[64:67], v[198:201], v[8:11]
	v_mfma_f32_16x16x32_bf16 v[84:87], v[60:63], v[164:167], v[84:87]
	v_mfma_f32_16x16x32_bf16 v[80:83], v[68:71], v[164:167], v[80:83]
	v_mfma_f32_16x16x32_bf16 v[44:47], v[60:63], v[172:175], v[44:47]
	v_mfma_f32_16x16x32_bf16 v[40:43], v[68:71], v[172:175], v[40:43]
	v_mfma_f32_16x16x32_bf16 v[28:31], v[60:63], v[194:197], v[28:31]
	v_mfma_f32_16x16x32_bf16 v[24:27], v[68:71], v[194:197], v[24:27]
	v_mfma_f32_16x16x32_bf16 v[12:15], v[60:63], v[202:205], v[12:15]
	v_mfma_f32_16x16x32_bf16 v[8:11], v[68:71], v[202:205], v[8:11]
	v_mfma_f32_16x16x32_bf16 v[52:55], v[72:75], v[160:163], v[52:55]
	v_mfma_f32_16x16x32_bf16 v[48:51], v[88:91], v[160:163], v[48:51]
	v_mfma_f32_16x16x32_bf16 v[36:39], v[72:75], v[168:171], v[36:39]
	v_mfma_f32_16x16x32_bf16 v[32:35], v[88:91], v[168:171], v[32:35]
	v_mfma_f32_16x16x32_bf16 v[20:23], v[72:75], v[190:193], v[20:23]
	v_mfma_f32_16x16x32_bf16 v[16:19], v[88:91], v[190:193], v[16:19]
	v_mfma_f32_16x16x32_bf16 v[4:7], v[72:75], v[198:201], v[4:7]
	v_mfma_f32_16x16x32_bf16 v[0:3], v[88:91], v[198:201], v[0:3]
	v_mfma_f32_16x16x32_bf16 v[60:63], v[76:79], v[164:167], v[52:55]
	v_mfma_f32_16x16x32_bf16 v[48:51], v[92:95], v[164:167], v[48:51]
	v_mfma_f32_16x16x32_bf16 v[36:39], v[76:79], v[172:175], v[36:39]
	v_mfma_f32_16x16x32_bf16 v[32:35], v[92:95], v[172:175], v[32:35]
	v_mfma_f32_16x16x32_bf16 v[20:23], v[76:79], v[194:197], v[20:23]
	v_mfma_f32_16x16x32_bf16 v[16:19], v[92:95], v[194:197], v[16:19]
	v_mfma_f32_16x16x32_bf16 v[4:7], v[76:79], v[202:205], v[4:7]
	v_mfma_f32_16x16x32_bf16 v[0:3], v[92:95], v[202:205], v[0:3]
	s_add_i32 s61, s61, 2
	s_add_u32 s36, s36, 0x100
	s_addc_u32 s37, s37, 0
	s_add_u32 s1, s1, 0x100
	s_addc_u32 s25, s25, 0
	s_cmp_gt_u32 s61, 29
	s_barrier
	s_cbranch_scc0 .LBB0_945
	s_setprio 0
	s_and_b64 vcc, exec, s[16:17]
	s_cbranch_vccz .LBB0_948
	s_barrier

; #define PG8_STAGE(bufoff, gbase, voff) do { _Pragma("unroll") for (int _i = 0; _i < 2; ++_i) \
;         __builtin_amdgcn_global_load_lds((const unsigned*)((const char*)(gbase) + (voff)[_i]), (LAS unsigned*)(lds + (bufoff) + ldsw + _i * 8192), 16, 0, 0); } while (0)
; #define PG8_LDA(dst, b, h) do { _Pragma("unroll") for (int m = 0; m < 4; ++m) _Pragma("unroll") for (int k = 0; k < 2; ++k) dst[m][k] = *(const LAS bf16x8*)(lds + PG8_SA(b, h) + aoff + m * 2048 + k * 1024); } while (0)
; #define PG8_LDB(dst, b, h) do { _Pragma("unroll") for (int n = 0; n < 2; ++n) _Pragma("unroll") for (int k = 0; k < 2; ++k) dst[n][k] = *(const LAS bf16x8*)(lds + PG8_SB(b, h) + boff + n * 2048 + k * 1024); } while (0)
; #define PG8_MMA(ai, bj, At, Bt) do { __builtin_amdgcn_s_setprio(1); _Pragma("unroll") for (int m = 0; m < 4; ++m) _Pragma("unroll") for (int n = 0; n < 2; ++n) _Pragma("unroll") for (int k = 0; k < 2; ++k) \
;         acc[ai][bj][m][n] = __builtin_amdgcn_mfma_f32_16x16x32_bf16(Bt[n][k], At[m][k], acc[ai][bj][m][n], 0, 0, 0); __builtin_amdgcn_s_setprio(0); } while (0)
; #define PG8_WAIT_V(n) asm volatile("s_waitcnt vmcnt(" #n ")" ::: "memory")
; #define PG8_WAIT_L(n) asm volatile("s_waitcnt lgkmcnt(" #n ")" ::: "memory")
; #define PG8_BAR __builtin_amdgcn_s_barrier()
; #define PG8_SCHED __builtin_amdgcn_sched_barrier(0)
; template <class Sched, class Epi, bool ALIGN_EPI, bool SP2>
; __device__ __forceinline__ void gemm_phase(LAS unsigned char* lds, const int K, const int lda, const int ldb, const Sched& S, const Epi& E) {
;     ...
;             PG8_LDB(B0, 0, 0); PG8_LDB(B1, 0, 1); PG8_SCHED; PG8_LDA(At, 0, 0); PG8_STAGE(PG8_SA(1, 1), a1 + hstepA, voffA);
;             PG8_WAIT_V(8); PG8_WAIT_L(0); PG8_BAR; PG8_MMA(0, 0, At, B0); PG8_MMA(0, 1, At, B1); PG8_BAR; PG8_SCHED;
;             PG8_LDA(At, 0, 1); PG8_STAGE(PG8_SB(0, 0), b2, voffB); PG8_STAGE(PG8_SB(0, 1), b2 + hstepB, voffB); PG8_STAGE(PG8_SA(0, 0), a2, voffA);
;             PG8_WAIT_V(8); PG8_WAIT_L(0); PG8_BAR; PG8_MMA(1, 0, At, B0); PG8_MMA(1, 1, At, B1); PG8_BAR; PG8_SCHED;
.LBB0_1037:
	ds_read_b128 v[64:67], v183
	ds_read_b128 v[68:71], v183 offset:1024
	ds_read_b128 v[72:75], v183 offset:2048
	ds_read_b128 v[76:79], v183 offset:3072
	ds_read_b128 v[144:147], v184
	ds_read_b128 v[160:163], v184 offset:1024
	ds_read_b128 v[164:167], v184 offset:2048
	ds_read_b128 v[168:171], v184 offset:3072
	s_add_u32 s42, s36, 0xfff80080
	s_addc_u32 s43, s37, -1
	s_cmp_eq_u32 s57, 28
	s_cselect_b32 s45, s27, s43
	s_cselect_b32 s44, s26, s42
	s_cselect_b32 s43, s29, s56
	s_cselect_b32 s42, s28, s25
	s_add_i32 m0, s33, 0xc000
	ds_read_b128 v[172:175], v185
	ds_read_b128 v[188:191], v185 offset:1024
	ds_read_b128 v[192:195], v185 offset:2048
	ds_read_b128 v[196:199], v185 offset:3072
	ds_read_b128 v[200:203], v185 offset:4096
	ds_read_b128 v[204:207], v185 offset:5120
	ds_read_b128 v[208:211], v185 offset:6144
	ds_read_b128 v[212:215], v185 offset:7168
	global_load_lds_dwordx4 v156, s[36:37]
	s_add_i32 m0, s33, 0xe000
	s_nop 0
	global_load_lds_dwordx4 v158, s[36:37]
	s_waitcnt vmcnt(8) lgkmcnt(0)
	s_barrier
	v_mfma_f32_16x16x32_bf16 v[140:143], v[64:67], v[172:175], v[140:143]
	v_mfma_f32_16x16x32_bf16 v[136:139], v[72:75], v[172:175], v[136:139]
	v_mfma_f32_16x16x32_bf16 v[124:127], v[64:67], v[192:195], v[124:127]
	v_mfma_f32_16x16x32_bf16 v[120:123], v[72:75], v[192:195], v[120:123]
	v_mfma_f32_16x16x32_bf16 v[108:111], v[64:67], v[200:203], v[108:111]
	v_mfma_f32_16x16x32_bf16 v[104:107], v[72:75], v[200:203], v[104:107]
	v_mfma_f32_16x16x32_bf16 v[92:95], v[64:67], v[208:211], v[92:95]
	v_mfma_f32_16x16x32_bf16 v[88:91], v[72:75], v[208:211], v[88:91]
	v_mfma_f32_16x16x32_bf16 v[140:143], v[68:71], v[188:191], v[140:143]
	v_mfma_f32_16x16x32_bf16 v[136:139], v[76:79], v[188:191], v[136:139]
	v_mfma_f32_16x16x32_bf16 v[124:127], v[68:71], v[196:199], v[124:127]
	v_mfma_f32_16x16x32_bf16 v[120:123], v[76:79], v[196:199], v[120:123]
	v_mfma_f32_16x16x32_bf16 v[108:111], v[68:71], v[204:207], v[108:111]
	v_mfma_f32_16x16x32_bf16 v[104:107], v[76:79], v[204:207], v[104:107]
	v_mfma_f32_16x16x32_bf16 v[92:95], v[68:71], v[212:215], v[92:95]
	v_mfma_f32_16x16x32_bf16 v[88:91], v[76:79], v[212:215], v[88:91]
	v_mfma_f32_16x16x32_bf16 v[132:135], v[144:147], v[172:175], v[132:135]
	v_mfma_f32_16x16x32_bf16 v[128:131], v[164:167], v[172:175], v[128:131]
	v_mfma_f32_16x16x32_bf16 v[116:119], v[144:147], v[192:195], v[116:119]
	v_mfma_f32_16x16x32_bf16 v[112:115], v[164:167], v[192:195], v[112:115]
	v_mfma_f32_16x16x32_bf16 v[100:103], v[144:147], v[200:203], v[100:103]
	v_mfma_f32_16x16x32_bf16 v[96:99], v[164:167], v[200:203], v[96:99]
	v_mfma_f32_16x16x32_bf16 v[84:87], v[144:147], v[208:211], v[84:87]
	v_mfma_f32_16x16x32_bf16 v[80:83], v[164:167], v[208:211], v[80:83]
	v_mfma_f32_16x16x32_bf16 v[132:135], v[160:163], v[188:191], v[132:135]
	v_mfma_f32_16x16x32_bf16 v[128:131], v[168:171], v[188:191], v[128:131]
	v_mfma_f32_16x16x32_bf16 v[116:119], v[160:163], v[196:199], v[116:119]
	v_mfma_f32_16x16x32_bf16 v[112:115], v[168:171], v[196:199], v[112:115]
	v_mfma_f32_16x16x32_bf16 v[100:103], v[160:163], v[204:207], v[100:103]
	v_mfma_f32_16x16x32_bf16 v[96:99], v[168:171], v[204:207], v[96:99]
	v_mfma_f32_16x16x32_bf16 v[84:87], v[160:163], v[212:215], v[84:87]
	v_mfma_f32_16x16x32_bf16 v[80:83], v[168:171], v[212:215], v[80:83]
	s_barrier
	s_add_i32 s58, s51, s21
	v_lshl_add_u64 v[216:217], s[42:43], 0, v[150:151]
	s_mov_b32 m0, s58
	ds_read_b128 v[172:175], v185 offset:16384
	ds_read_b128 v[188:191], v185 offset:17408
	ds_read_b128 v[192:195], v185 offset:18432
	ds_read_b128 v[196:199], v185 offset:19456
	ds_read_b128 v[200:203], v185 offset:20480
	ds_read_b128 v[204:207], v185 offset:21504
	ds_read_b128 v[208:211], v185 offset:22528
	ds_read_b128 v[212:215], v185 offset:23552
	global_load_lds_dwordx4 v[216:217], off
	s_add_i32 m0, s58, 0x2000
	s_add_u32 s58, s42, 0x80000
	v_lshl_add_u64 v[218:219], s[42:43], 0, v[154:155]
	s_addc_u32 s59, s43, 0
	s_add_i32 s60, s52, s21
	global_load_lds_dwordx4 v[218:219], off
	s_mov_b32 m0, s60
	v_lshl_add_u64 v[222:223], s[44:45], 0, v[152:153]
	global_load_lds_dwordx4 v150, s[58:59]
	s_add_i32 m0, s60, 0x2000
	s_nop 0
	global_load_lds_dwordx4 v154, s[58:59]
	v_lshl_add_u64 v[220:221], s[44:45], 0, v[148:149]
	s_mov_b32 m0, s33
	s_nop 0
	global_load_lds_dwordx4 v[220:221], off
	s_mov_b32 m0, s35
	s_nop 0
	global_load_lds_dwordx4 v[222:223], off
	s_waitcnt vmcnt(8) lgkmcnt(0)
	s_barrier
	v_mfma_f32_16x16x32_bf16 v[60:63], v[64:67], v[172:175], v[60:63]
	v_mfma_f32_16x16x32_bf16 v[56:59], v[72:75], v[172:175], v[56:59]
	v_mfma_f32_16x16x32_bf16 v[44:47], v[64:67], v[192:195], v[44:47]
	v_mfma_f32_16x16x32_bf16 v[40:43], v[72:75], v[192:195], v[40:43]
	v_mfma_f32_16x16x32_bf16 v[24:27], v[64:67], v[200:203], v[24:27]
	v_mfma_f32_16x16x32_bf16 v[20:23], v[72:75], v[200:203], v[20:23]
	v_mfma_f32_16x16x32_bf16 v[8:11], v[64:67], v[208:211], v[8:11]
	v_mfma_f32_16x16x32_bf16 v[0:3], v[72:75], v[208:211], v[0:3]
	v_mfma_f32_16x16x32_bf16 v[60:63], v[68:71], v[188:191], v[60:63]
	v_mfma_f32_16x16x32_bf16 v[56:59], v[76:79], v[188:191], v[56:59]
	v_mfma_f32_16x16x32_bf16 v[44:47], v[68:71], v[196:199], v[44:47]
	v_mfma_f32_16x16x32_bf16 v[40:43], v[76:79], v[196:199], v[40:43]
	v_mfma_f32_16x16x32_bf16 v[24:27], v[68:71], v[204:207], v[24:27]
	v_mfma_f32_16x16x32_bf16 v[20:23], v[76:79], v[204:207], v[20:23]
	v_mfma_f32_16x16x32_bf16 v[8:11], v[68:71], v[212:215], v[8:11]
	v_mfma_f32_16x16x32_bf16 v[0:3], v[76:79], v[212:215], v[0:3]
	v_mfma_f32_16x16x32_bf16 v[52:55], v[144:147], v[172:175], v[52:55]
	v_mfma_f32_16x16x32_bf16 v[48:51], v[164:167], v[172:175], v[48:51]
	v_mfma_f32_16x16x32_bf16 v[36:39], v[144:147], v[192:195], v[36:39]
	v_mfma_f32_16x16x32_bf16 v[32:35], v[164:167], v[192:195], v[32:35]
	v_mfma_f32_16x16x32_bf16 v[28:31], v[144:147], v[200:203], v[28:31]
	v_mfma_f32_16x16x32_bf16 v[16:19], v[164:167], v[200:203], v[16:19]
	v_mfma_f32_16x16x32_bf16 v[12:15], v[144:147], v[208:211], v[12:15]
	v_mfma_f32_16x16x32_bf16 v[4:7], v[164:167], v[208:211], v[4:7]
	v_mfma_f32_16x16x32_bf16 v[52:55], v[160:163], v[188:191], v[52:55]
	v_mfma_f32_16x16x32_bf16 v[48:51], v[168:171], v[188:191], v[48:51]
	v_mfma_f32_16x16x32_bf16 v[36:39], v[160:163], v[196:199], v[36:39]
	v_mfma_f32_16x16x32_bf16 v[32:35], v[168:171], v[196:199], v[32:35]
	v_mfma_f32_16x16x32_bf16 v[28:31], v[160:163], v[204:207], v[28:31]
	v_mfma_f32_16x16x32_bf16 v[16:19], v[168:171], v[204:207], v[16:19]
	v_mfma_f32_16x16x32_bf16 v[12:15], v[160:163], v[212:215], v[12:15]
	v_mfma_f32_16x16x32_bf16 v[4:7], v[168:171], v[212:215], v[4:7]
	s_barrier
; #define PG8_STAGE(bufoff, gbase, voff) do { _Pragma("unroll") for (int _i = 0; _i < 2; ++_i) \
;         __builtin_amdgcn_global_load_lds((const unsigned*)((const char*)(gbase) + (voff)[_i]), (LAS unsigned*)(lds + (bufoff) + ldsw + _i * 8192), 16, 0, 0); } while (0)
; #define PG8_LDA(dst, b, h) do { _Pragma("unroll") for (int m = 0; m < 4; ++m) _Pragma("unroll") for (int k = 0; k < 2; ++k) dst[m][k] = *(const LAS bf16x8*)(lds + PG8_SA(b, h) + aoff + m * 2048 + k * 1024); } while (0)
; #define PG8_LDB(dst, b, h) do { _Pragma("unroll") for (int n = 0; n < 2; ++n) _Pragma("unroll") for (int k = 0; k < 2; ++k) dst[n][k] = *(const LAS bf16x8*)(lds + PG8_SB(b, h) + boff + n * 2048 + k * 1024); } while (0)
; #define PG8_MMA(ai, bj, At, Bt) do { __builtin_amdgcn_s_setprio(1); _Pragma("unroll") for (int m = 0; m < 4; ++m) _Pragma("unroll") for (int n = 0; n < 2; ++n) _Pragma("unroll") for (int k = 0; k < 2; ++k) \
;         acc[ai][bj][m][n] = __builtin_amdgcn_mfma_f32_16x16x32_bf16(Bt[n][k], At[m][k], acc[ai][bj][m][n], 0, 0, 0); __builtin_amdgcn_s_setprio(0); } while (0)
; #define PG8_WAIT_V(n) asm volatile("s_waitcnt vmcnt(" #n ")" ::: "memory")
; #define PG8_WAIT_L(n) asm volatile("s_waitcnt lgkmcnt(" #n ")" ::: "memory")
; #define PG8_BAR __builtin_amdgcn_s_barrier()
; template <class Sched, class Epi, bool ALIGN_EPI, bool SP2>
; __device__ __forceinline__ void gemm_phase(LAS unsigned char* lds, const int K, const int lda, const int ldb, const Sched& S, const Epi& E) {
;     ...
;         for (int t = 0; t < nt; t += 2) {
;             const bool last = (t == nt - 2);
;             const char* a1 = cA + (size_t)(t + 1) * kstep;
;             const char* a2 = last ? nA : cA + (size_t)(t + 2) * kstep; const char* b2 = last ? nB : cB + (size_t)(t + 2) * kstep;
;             const char* a3 = a2 + kstep; const char* b3 = b2 + kstep;
;     ...
;             PG8_LDB(B0, 1, 0); PG8_LDB(B1, 1, 1); PG8_SCHED; PG8_LDA(At, 1, 0); PG8_STAGE(PG8_SA(0, 1), a2 + hstepA, voffA);
;             PG8_WAIT_V(8); PG8_WAIT_L(0); PG8_BAR; PG8_MMA(0, 0, At, B0); PG8_MMA(0, 1, At, B1); PG8_BAR; PG8_SCHED;
;             PG8_LDA(At, 1, 1); PG8_STAGE(PG8_SB(1, 0), b3, voffB); PG8_STAGE(PG8_SB(1, 1), b3 + hstepB, voffB); PG8_STAGE(PG8_SA(1, 0), a3, voffA);
;             PG8_WAIT_V(8); PG8_WAIT_L(0); PG8_BAR; PG8_MMA(1, 0, At, B0); PG8_MMA(1, 1, At, B1); PG8_BAR; PG8_SCHED;
	s_add_i32 s58, 0, 0x18000
	s_add_i32 s59, 0, 0x1c000
	v_add_u32_e32 v76, s58, v181
	v_add_u32_e32 v168, s59, v181
	ds_read_b128 v[64:67], v76
	ds_read_b128 v[68:71], v76 offset:1024
	ds_read_b128 v[72:75], v76 offset:2048
	ds_read_b128 v[76:79], v76 offset:3072
	ds_read_b128 v[144:147], v168
	ds_read_b128 v[160:163], v168 offset:1024
	ds_read_b128 v[164:167], v168 offset:2048
	ds_read_b128 v[168:171], v168 offset:3072
	s_add_u32 s44, s44, 0x80000
	s_addc_u32 s45, s45, 0
	s_mov_b32 m0, s46
	ds_read_b128 v[172:175], v185 offset:32768
	ds_read_b128 v[188:191], v185 offset:33792
	ds_read_b128 v[192:195], v185 offset:34816
	ds_read_b128 v[196:199], v185 offset:35840
	ds_read_b128 v[200:203], v185 offset:36864
	ds_read_b128 v[204:207], v185 offset:37888
	ds_read_b128 v[208:211], v185 offset:38912
	ds_read_b128 v[212:215], v185 offset:39936
	global_load_lds_dwordx4 v148, s[44:45]
	s_mov_b32 m0, s47
	s_nop 0
	global_load_lds_dwordx4 v152, s[44:45]
	s_waitcnt vmcnt(8) lgkmcnt(0)
	s_barrier
	v_mfma_f32_16x16x32_bf16 v[140:143], v[64:67], v[172:175], v[140:143]
	v_mfma_f32_16x16x32_bf16 v[136:139], v[72:75], v[172:175], v[136:139]
	v_mfma_f32_16x16x32_bf16 v[124:127], v[64:67], v[192:195], v[124:127]
	v_mfma_f32_16x16x32_bf16 v[120:123], v[72:75], v[192:195], v[120:123]
	v_mfma_f32_16x16x32_bf16 v[108:111], v[64:67], v[200:203], v[108:111]
	v_mfma_f32_16x16x32_bf16 v[104:107], v[72:75], v[200:203], v[104:107]
	v_mfma_f32_16x16x32_bf16 v[92:95], v[64:67], v[208:211], v[92:95]
	v_mfma_f32_16x16x32_bf16 v[88:91], v[72:75], v[208:211], v[88:91]
	v_mfma_f32_16x16x32_bf16 v[140:143], v[68:71], v[188:191], v[140:143]
	v_mfma_f32_16x16x32_bf16 v[136:139], v[76:79], v[188:191], v[136:139]
	v_mfma_f32_16x16x32_bf16 v[124:127], v[68:71], v[196:199], v[124:127]
	v_mfma_f32_16x16x32_bf16 v[120:123], v[76:79], v[196:199], v[120:123]
	v_mfma_f32_16x16x32_bf16 v[108:111], v[68:71], v[204:207], v[108:111]
	v_mfma_f32_16x16x32_bf16 v[104:107], v[76:79], v[204:207], v[104:107]
	v_mfma_f32_16x16x32_bf16 v[92:95], v[68:71], v[212:215], v[92:95]
	v_mfma_f32_16x16x32_bf16 v[88:91], v[76:79], v[212:215], v[88:91]
	v_mfma_f32_16x16x32_bf16 v[132:135], v[144:147], v[172:175], v[132:135]
	v_mfma_f32_16x16x32_bf16 v[128:131], v[164:167], v[172:175], v[128:131]
	v_mfma_f32_16x16x32_bf16 v[116:119], v[144:147], v[192:195], v[116:119]
	v_mfma_f32_16x16x32_bf16 v[112:115], v[164:167], v[192:195], v[112:115]
	v_mfma_f32_16x16x32_bf16 v[100:103], v[144:147], v[200:203], v[100:103]
	v_mfma_f32_16x16x32_bf16 v[96:99], v[164:167], v[200:203], v[96:99]
	v_mfma_f32_16x16x32_bf16 v[84:87], v[144:147], v[208:211], v[84:87]
	v_mfma_f32_16x16x32_bf16 v[80:83], v[164:167], v[208:211], v[80:83]
	v_mfma_f32_16x16x32_bf16 v[132:135], v[160:163], v[188:191], v[132:135]
	v_mfma_f32_16x16x32_bf16 v[128:131], v[168:171], v[188:191], v[128:131]
	v_mfma_f32_16x16x32_bf16 v[116:119], v[160:163], v[196:199], v[116:119]
	v_mfma_f32_16x16x32_bf16 v[112:115], v[168:171], v[196:199], v[112:115]
	v_mfma_f32_16x16x32_bf16 v[100:103], v[160:163], v[204:207], v[100:103]
	v_mfma_f32_16x16x32_bf16 v[96:99], v[168:171], v[204:207], v[96:99]
	v_mfma_f32_16x16x32_bf16 v[84:87], v[160:163], v[212:215], v[84:87]
	v_mfma_f32_16x16x32_bf16 v[80:83], v[168:171], v[212:215], v[80:83]
	s_barrier
	s_add_i32 s44, s58, s21
	v_lshl_add_u64 v[216:217], v[216:217], 0, s[14:15]
	s_mov_b32 m0, s44
	ds_read_b128 v[172:175], v185 offset:49152
	ds_read_b128 v[188:191], v185 offset:50176
	ds_read_b128 v[192:195], v185 offset:51200
	ds_read_b128 v[196:199], v185 offset:52224
	ds_read_b128 v[200:203], v185 offset:53248
	ds_read_b128 v[204:207], v185 offset:54272
	ds_read_b128 v[208:211], v185 offset:55296
	ds_read_b128 v[212:215], v185 offset:56320
	global_load_lds_dwordx4 v[216:217], off
	s_add_i32 m0, s44, 0x2000
	s_add_u32 s42, s42, 0x80080
	v_lshl_add_u64 v[216:217], v[218:219], 0, s[14:15]
	s_addc_u32 s43, s43, 0
	s_add_i32 s44, s59, s21
	global_load_lds_dwordx4 v[216:217], off
	s_mov_b32 m0, s44
	s_nop 0
	global_load_lds_dwordx4 v150, s[42:43]
	s_add_i32 m0, s44, 0x2000
	s_nop 0
	global_load_lds_dwordx4 v154, s[42:43]
	v_lshl_add_u64 v[216:217], v[220:221], 0, s[14:15]
	s_mov_b32 m0, s49
	s_nop 0
	global_load_lds_dwordx4 v[216:217], off
	v_lshl_add_u64 v[216:217], v[222:223], 0, s[14:15]
	s_mov_b32 m0, s50
	s_nop 0
	global_load_lds_dwordx4 v[216:217], off
	s_waitcnt vmcnt(8) lgkmcnt(0)
	s_barrier
	v_mfma_f32_16x16x32_bf16 v[60:63], v[64:67], v[172:175], v[60:63]
	v_mfma_f32_16x16x32_bf16 v[56:59], v[72:75], v[172:175], v[56:59]
	v_mfma_f32_16x16x32_bf16 v[44:47], v[64:67], v[192:195], v[44:47]
	v_mfma_f32_16x16x32_bf16 v[40:43], v[72:75], v[192:195], v[40:43]
	v_mfma_f32_16x16x32_bf16 v[24:27], v[64:67], v[200:203], v[24:27]
	v_mfma_f32_16x16x32_bf16 v[20:23], v[72:75], v[200:203], v[20:23]
	v_mfma_f32_16x16x32_bf16 v[8:11], v[64:67], v[208:211], v[8:11]
	v_mfma_f32_16x16x32_bf16 v[0:3], v[72:75], v[208:211], v[0:3]
	v_mfma_f32_16x16x32_bf16 v[60:63], v[68:71], v[188:191], v[60:63]
	v_mfma_f32_16x16x32_bf16 v[56:59], v[76:79], v[188:191], v[56:59]
	v_mfma_f32_16x16x32_bf16 v[44:47], v[68:71], v[196:199], v[44:47]
	v_mfma_f32_16x16x32_bf16 v[40:43], v[76:79], v[196:199], v[40:43]
	v_mfma_f32_16x16x32_bf16 v[24:27], v[68:71], v[204:207], v[24:27]
	v_mfma_f32_16x16x32_bf16 v[20:23], v[76:79], v[204:207], v[20:23]
	v_mfma_f32_16x16x32_bf16 v[8:11], v[68:71], v[212:215], v[8:11]
	v_mfma_f32_16x16x32_bf16 v[0:3], v[76:79], v[212:215], v[0:3]
	v_mfma_f32_16x16x32_bf16 v[52:55], v[144:147], v[172:175], v[52:55]
	v_mfma_f32_16x16x32_bf16 v[48:51], v[164:167], v[172:175], v[48:51]
	v_mfma_f32_16x16x32_bf16 v[36:39], v[144:147], v[192:195], v[36:39]
	v_mfma_f32_16x16x32_bf16 v[32:35], v[164:167], v[192:195], v[32:35]
	v_mfma_f32_16x16x32_bf16 v[28:31], v[144:147], v[200:203], v[28:31]
	v_mfma_f32_16x16x32_bf16 v[16:19], v[164:167], v[200:203], v[16:19]
	v_mfma_f32_16x16x32_bf16 v[12:15], v[144:147], v[208:211], v[12:15]
	v_mfma_f32_16x16x32_bf16 v[4:7], v[164:167], v[208:211], v[4:7]
	v_mfma_f32_16x16x32_bf16 v[52:55], v[160:163], v[188:191], v[52:55]
	v_mfma_f32_16x16x32_bf16 v[48:51], v[168:171], v[188:191], v[48:51]
	v_mfma_f32_16x16x32_bf16 v[36:39], v[160:163], v[196:199], v[36:39]
	v_mfma_f32_16x16x32_bf16 v[32:35], v[168:171], v[196:199], v[32:35]
	v_mfma_f32_16x16x32_bf16 v[28:31], v[160:163], v[204:207], v[28:31]
	v_mfma_f32_16x16x32_bf16 v[16:19], v[168:171], v[204:207], v[16:19]
	v_mfma_f32_16x16x32_bf16 v[12:15], v[160:163], v[212:215], v[12:15]
	v_mfma_f32_16x16x32_bf16 v[4:7], v[168:171], v[212:215], v[4:7]
	s_add_i32 s57, s57, 2
	s_add_u32 s36, s36, 0x100
	s_addc_u32 s37, s37, 0
	s_add_u32 s25, s25, 0x100
	s_addc_u32 s56, s56, 0
	s_cmp_gt_u32 s57, 29
	s_barrier
	s_cbranch_scc0 .LBB0_1037
	s_setprio 0
	s_and_b64 vcc, exec, s[16:17]
	s_mov_b32 s56, s62
	s_cbranch_vccz .LBB0_1040
	s_barrier

; #define PG8_STAGE(bufoff, gbase, voff) do { _Pragma("unroll") for (int _i = 0; _i < 2; ++_i) \
;         __builtin_amdgcn_global_load_lds((const unsigned*)((const char*)(gbase) + (voff)[_i]), (LAS unsigned*)(lds + (bufoff) + ldsw + _i * 8192), 16, 0, 0); } while (0)
; #define PG8_LDA(dst, b, h) do { _Pragma("unroll") for (int m = 0; m < 4; ++m) _Pragma("unroll") for (int k = 0; k < 2; ++k) dst[m][k] = *(const LAS bf16x8*)(lds + PG8_SA(b, h) + aoff + m * 2048 + k * 1024); } while (0)
; #define PG8_LDB(dst, b, h) do { _Pragma("unroll") for (int n = 0; n < 2; ++n) _Pragma("unroll") for (int k = 0; k < 2; ++k) dst[n][k] = *(const LAS bf16x8*)(lds + PG8_SB(b, h) + boff + n * 2048 + k * 1024); } while (0)
; #define PG8_MMA(ai, bj, At, Bt) do { __builtin_amdgcn_s_setprio(1); _Pragma("unroll") for (int m = 0; m < 4; ++m) _Pragma("unroll") for (int n = 0; n < 2; ++n) _Pragma("unroll") for (int k = 0; k < 2; ++k) \
;         acc[ai][bj][m][n] = __builtin_amdgcn_mfma_f32_16x16x32_bf16(Bt[n][k], At[m][k], acc[ai][bj][m][n], 0, 0, 0); __builtin_amdgcn_s_setprio(0); } while (0)
; #define PG8_WAIT_V(n) asm volatile("s_waitcnt vmcnt(" #n ")" ::: "memory")
; #define PG8_WAIT_L(n) asm volatile("s_waitcnt lgkmcnt(" #n ")" ::: "memory")
; #define PG8_BAR __builtin_amdgcn_s_barrier()
; #define PG8_SCHED __builtin_amdgcn_sched_barrier(0)
; template <class Sched, class Epi, bool ALIGN_EPI, bool SP2>
; __device__ __forceinline__ void gemm_phase(LAS unsigned char* lds, const int K, const int lda, const int ldb, const Sched& S, const Epi& E) {
;     ...
;             PG8_LDB(B0, 0, 0); PG8_LDB(B1, 0, 1); PG8_SCHED; PG8_LDA(At, 0, 0); PG8_STAGE(PG8_SA(1, 1), a1 + hstepA, voffA);
;             PG8_WAIT_V(8); PG8_WAIT_L(0); PG8_BAR; PG8_MMA(0, 0, At, B0); PG8_MMA(0, 1, At, B1); PG8_BAR; PG8_SCHED;
;             PG8_LDA(At, 0, 1); PG8_STAGE(PG8_SB(0, 0), b2, voffB); PG8_STAGE(PG8_SB(0, 1), b2 + hstepB, voffB); PG8_STAGE(PG8_SA(0, 0), a2, voffA);
;             PG8_WAIT_V(8); PG8_WAIT_L(0); PG8_BAR; PG8_MMA(1, 0, At, B0); PG8_MMA(1, 1, At, B1); PG8_BAR; PG8_SCHED;
.LBB0_1120:
	ds_read_b128 v[96:99], v178
	ds_read_b128 v[100:103], v178 offset:1024
	ds_read_b128 v[104:107], v178 offset:2048
	ds_read_b128 v[108:111], v178 offset:3072
	ds_read_b128 v[112:115], v180
	ds_read_b128 v[116:119], v180 offset:1024
	ds_read_b128 v[120:123], v180 offset:2048
	ds_read_b128 v[124:127], v180 offset:3072
	s_add_u32 s4, s0, 0x100
	s_addc_u32 s5, s1, 0
	s_cmpk_eq_i32 s51, 0x54
	s_cselect_b32 s27, s21, s5
	s_cselect_b32 s26, s20, s4
	s_cselect_b32 s25, s23, s50
	s_cselect_b32 s24, s22, s49
	s_add_i32 m0, s17, 0xc000
	ds_read_b128 v[168:171], v181
	ds_read_b128 v[184:187], v181 offset:1024
	ds_read_b128 v[188:191], v181 offset:2048
	ds_read_b128 v[192:195], v181 offset:3072
	ds_read_b128 v[196:199], v181 offset:4096
	ds_read_b128 v[200:203], v181 offset:5120
	ds_read_b128 v[204:207], v181 offset:6144
	ds_read_b128 v[208:211], v181 offset:7168
	global_load_lds_dwordx4 v164, s[0:1]
	s_add_i32 m0, s17, 0xe000
	s_nop 0
	global_load_lds_dwordx4 v166, s[0:1]
	s_waitcnt vmcnt(8) lgkmcnt(0)
	s_barrier
	v_mfma_f32_16x16x32_bf16 v[156:159], v[96:99], v[168:171], v[156:159]
	v_mfma_f32_16x16x32_bf16 v[152:155], v[104:107], v[168:171], v[152:155]
	v_mfma_f32_16x16x32_bf16 v[144:147], v[96:99], v[188:191], v[144:147]
	v_mfma_f32_16x16x32_bf16 v[136:139], v[104:107], v[188:191], v[136:139]
	v_mfma_f32_16x16x32_bf16 v[92:95], v[96:99], v[196:199], v[92:95]
	v_mfma_f32_16x16x32_bf16 v[88:91], v[104:107], v[196:199], v[88:91]
	v_mfma_f32_16x16x32_bf16 v[80:83], v[96:99], v[204:207], v[80:83]
	v_mfma_f32_16x16x32_bf16 v[72:75], v[104:107], v[204:207], v[72:75]
	v_mfma_f32_16x16x32_bf16 v[156:159], v[100:103], v[184:187], v[156:159]
	v_mfma_f32_16x16x32_bf16 v[152:155], v[108:111], v[184:187], v[152:155]
	v_mfma_f32_16x16x32_bf16 v[144:147], v[100:103], v[192:195], v[144:147]
	v_mfma_f32_16x16x32_bf16 v[136:139], v[108:111], v[192:195], v[136:139]
	v_mfma_f32_16x16x32_bf16 v[92:95], v[100:103], v[200:203], v[92:95]
	v_mfma_f32_16x16x32_bf16 v[88:91], v[108:111], v[200:203], v[88:91]
	v_mfma_f32_16x16x32_bf16 v[80:83], v[100:103], v[208:211], v[80:83]
	v_mfma_f32_16x16x32_bf16 v[72:75], v[108:111], v[208:211], v[72:75]
	v_mfma_f32_16x16x32_bf16 v[148:151], v[112:115], v[168:171], v[148:151]
	v_mfma_f32_16x16x32_bf16 v[140:143], v[120:123], v[168:171], v[140:143]
	v_mfma_f32_16x16x32_bf16 v[132:135], v[112:115], v[188:191], v[132:135]
	v_mfma_f32_16x16x32_bf16 v[128:131], v[120:123], v[188:191], v[128:131]
	v_mfma_f32_16x16x32_bf16 v[84:87], v[112:115], v[196:199], v[84:87]
	v_mfma_f32_16x16x32_bf16 v[76:79], v[120:123], v[196:199], v[76:79]
	v_mfma_f32_16x16x32_bf16 v[68:71], v[112:115], v[204:207], v[68:71]
	v_mfma_f32_16x16x32_bf16 v[64:67], v[120:123], v[204:207], v[64:67]
	v_mfma_f32_16x16x32_bf16 v[148:151], v[116:119], v[184:187], v[148:151]
	v_mfma_f32_16x16x32_bf16 v[140:143], v[124:127], v[184:187], v[140:143]
	v_mfma_f32_16x16x32_bf16 v[132:135], v[116:119], v[192:195], v[132:135]
	v_mfma_f32_16x16x32_bf16 v[128:131], v[124:127], v[192:195], v[128:131]
	v_mfma_f32_16x16x32_bf16 v[84:87], v[116:119], v[200:203], v[84:87]
	v_mfma_f32_16x16x32_bf16 v[76:79], v[124:127], v[200:203], v[76:79]
	v_mfma_f32_16x16x32_bf16 v[68:71], v[116:119], v[208:211], v[68:71]
	v_mfma_f32_16x16x32_bf16 v[64:67], v[124:127], v[208:211], v[64:67]
	s_barrier
	s_add_i32 s0, s42, s15
	v_lshl_add_u64 v[172:173], s[24:25], 0, v[160:161]
	s_mov_b32 m0, s0
	ds_read_b128 v[168:171], v181 offset:16384
	ds_read_b128 v[184:187], v181 offset:17408
	ds_read_b128 v[188:191], v181 offset:18432
	ds_read_b128 v[192:195], v181 offset:19456
	ds_read_b128 v[196:199], v181 offset:20480
	ds_read_b128 v[200:203], v181 offset:21504
	ds_read_b128 v[204:207], v181 offset:22528
	ds_read_b128 v[208:211], v181 offset:23552
	global_load_lds_dwordx4 v[172:173], off
	s_add_i32 m0, s0, 0x2000
	s_add_u32 s0, s24, 0x160000
	v_lshl_add_u64 v[212:213], s[24:25], 0, v[162:163]
	s_addc_u32 s1, s25, 0
	s_add_i32 s52, s43, s15
	global_load_lds_dwordx4 v[212:213], off
	s_mov_b32 m0, s52
	v_lshl_add_u64 v[216:217], s[26:27], 0, v[162:163]
	global_load_lds_dwordx4 v160, s[0:1]
	s_add_i32 m0, s52, 0x2000
	s_nop 0
	global_load_lds_dwordx4 v162, s[0:1]
	v_lshl_add_u64 v[214:215], s[26:27], 0, v[160:161]
	s_mov_b32 m0, s17
	s_nop 0
	global_load_lds_dwordx4 v[214:215], off
	s_mov_b32 m0, s28
	s_nop 0
	global_load_lds_dwordx4 v[216:217], off
	s_waitcnt vmcnt(8) lgkmcnt(0)
	s_barrier
	v_mfma_f32_16x16x32_bf16 v[60:63], v[96:99], v[168:171], v[60:63]
	v_mfma_f32_16x16x32_bf16 v[56:59], v[104:107], v[168:171], v[56:59]
	v_mfma_f32_16x16x32_bf16 v[48:51], v[96:99], v[188:191], v[48:51]
	v_mfma_f32_16x16x32_bf16 v[40:43], v[104:107], v[188:191], v[40:43]
	v_mfma_f32_16x16x32_bf16 v[28:31], v[96:99], v[196:199], v[28:31]
	v_mfma_f32_16x16x32_bf16 v[24:27], v[104:107], v[196:199], v[24:27]
	v_mfma_f32_16x16x32_bf16 v[16:19], v[96:99], v[204:207], v[16:19]
	v_mfma_f32_16x16x32_bf16 v[8:11], v[104:107], v[204:207], v[8:11]
	v_mfma_f32_16x16x32_bf16 v[60:63], v[100:103], v[184:187], v[60:63]
	v_mfma_f32_16x16x32_bf16 v[56:59], v[108:111], v[184:187], v[56:59]
	v_mfma_f32_16x16x32_bf16 v[48:51], v[100:103], v[192:195], v[48:51]
	v_mfma_f32_16x16x32_bf16 v[40:43], v[108:111], v[192:195], v[40:43]
	v_mfma_f32_16x16x32_bf16 v[28:31], v[100:103], v[200:203], v[28:31]
	v_mfma_f32_16x16x32_bf16 v[24:27], v[108:111], v[200:203], v[24:27]
	v_mfma_f32_16x16x32_bf16 v[16:19], v[100:103], v[208:211], v[16:19]
	v_mfma_f32_16x16x32_bf16 v[8:11], v[108:111], v[208:211], v[8:11]
	v_mfma_f32_16x16x32_bf16 v[52:55], v[112:115], v[168:171], v[52:55]
	v_mfma_f32_16x16x32_bf16 v[44:47], v[120:123], v[168:171], v[44:47]
	v_mfma_f32_16x16x32_bf16 v[36:39], v[112:115], v[188:191], v[36:39]
	v_mfma_f32_16x16x32_bf16 v[32:35], v[120:123], v[188:191], v[32:35]
	v_mfma_f32_16x16x32_bf16 v[20:23], v[112:115], v[196:199], v[20:23]
	v_mfma_f32_16x16x32_bf16 v[12:15], v[120:123], v[196:199], v[12:15]
	v_mfma_f32_16x16x32_bf16 v[4:7], v[112:115], v[204:207], v[4:7]
	v_mfma_f32_16x16x32_bf16 v[0:3], v[120:123], v[204:207], v[0:3]
	v_mfma_f32_16x16x32_bf16 v[52:55], v[116:119], v[184:187], v[52:55]
	v_mfma_f32_16x16x32_bf16 v[44:47], v[124:127], v[184:187], v[44:47]
	v_mfma_f32_16x16x32_bf16 v[36:39], v[116:119], v[192:195], v[36:39]
	v_mfma_f32_16x16x32_bf16 v[32:35], v[124:127], v[192:195], v[32:35]
	v_mfma_f32_16x16x32_bf16 v[20:23], v[116:119], v[200:203], v[20:23]
	v_mfma_f32_16x16x32_bf16 v[12:15], v[124:127], v[200:203], v[12:15]
	v_mfma_f32_16x16x32_bf16 v[4:7], v[116:119], v[208:211], v[4:7]
	v_mfma_f32_16x16x32_bf16 v[0:3], v[124:127], v[208:211], v[0:3]
	s_barrier
; #define PG8_STAGE(bufoff, gbase, voff) do { _Pragma("unroll") for (int _i = 0; _i < 2; ++_i) \
;         __builtin_amdgcn_global_load_lds((const unsigned*)((const char*)(gbase) + (voff)[_i]), (LAS unsigned*)(lds + (bufoff) + ldsw + _i * 8192), 16, 0, 0); } while (0)
; #define PG8_LDA(dst, b, h) do { _Pragma("unroll") for (int m = 0; m < 4; ++m) _Pragma("unroll") for (int k = 0; k < 2; ++k) dst[m][k] = *(const LAS bf16x8*)(lds + PG8_SA(b, h) + aoff + m * 2048 + k * 1024); } while (0)
; #define PG8_LDB(dst, b, h) do { _Pragma("unroll") for (int n = 0; n < 2; ++n) _Pragma("unroll") for (int k = 0; k < 2; ++k) dst[n][k] = *(const LAS bf16x8*)(lds + PG8_SB(b, h) + boff + n * 2048 + k * 1024); } while (0)
; #define PG8_BAR __builtin_amdgcn_s_barrier()
; template <class Sched, class Epi, bool ALIGN_EPI, bool SP2>
; __device__ __forceinline__ void gemm_phase(LAS unsigned char* lds, const int K, const int lda, const int ldb, const Sched& S, const Epi& E) {
;     ...
;         for (int t = 0; t < nt; t += 2) {
;             const bool last = (t == nt - 2);
;             const char* a1 = cA + (size_t)(t + 1) * kstep;
;             const char* a2 = last ? nA : cA + (size_t)(t + 2) * kstep; const char* b2 = last ? nB : cB + (size_t)(t + 2) * kstep;
;             const char* a3 = a2 + kstep; const char* b3 = b2 + kstep;
;             if constexpr (SP2) {
;             PG8_LDB(B0, 0, 0); PG8_LDB(B1, 0, 1); PG8_SCHED; PG8_LDA(At, 0, 0); PG8_STAGE(PG8_SA(1, 1), a1 + hstepA, voffA);
;             PG8_WAIT_V(8); PG8_WAIT_L(0); PG8_BAR; PG8_MMA(0, 0, At, B0); PG8_MMA(0, 1, At, B1); PG8_BAR; PG8_SCHED;
;             PG8_LDA(At, 0, 1); PG8_STAGE(PG8_SB(0, 0), b2, voffB); PG8_STAGE(PG8_SB(0, 1), b2 + hstepB, voffB); PG8_STAGE(PG8_SA(0, 0), a2, voffA);
;             PG8_WAIT_V(8); PG8_WAIT_L(0); PG8_BAR; PG8_MMA(1, 0, At, B0); PG8_MMA(1, 1, At, B1); PG8_BAR; PG8_SCHED;
;             PG8_LDB(B0, 1, 0); PG8_LDB(B1, 1, 1); PG8_SCHED; PG8_LDA(At, 1, 0); PG8_STAGE(PG8_SA(0, 1), a2 + hstepA, voffA);
;             PG8_WAIT_V(8); PG8_WAIT_L(0); PG8_BAR; PG8_MMA(0, 0, At, B0); PG8_MMA(0, 1, At, B1); PG8_BAR; PG8_SCHED;
;             PG8_LDA(At, 1, 1); PG8_STAGE(PG8_SB(1, 0), b3, voffB); PG8_STAGE(PG8_SB(1, 1), b3 + hstepB, voffB); PG8_STAGE(PG8_SA(1, 0), a3, voffA);
;             PG8_WAIT_V(8); PG8_WAIT_L(0); PG8_BAR; PG8_MMA(1, 0, At, B0); PG8_MMA(1, 1, At, B1); PG8_BAR; PG8_SCHED;
	s_add_i32 s52, 0, 0x18000
	s_add_i32 s53, 0, 0x1c000
	v_add_u32_e32 v108, s52, v175
	v_add_u32_e32 v124, s53, v175
	ds_read_b128 v[96:99], v108
	ds_read_b128 v[100:103], v108 offset:1024
	ds_read_b128 v[104:107], v108 offset:2048
	ds_read_b128 v[108:111], v108 offset:3072
	ds_read_b128 v[112:115], v124
	ds_read_b128 v[116:119], v124 offset:1024
	ds_read_b128 v[120:123], v124 offset:2048
	ds_read_b128 v[124:127], v124 offset:3072
	s_add_u32 s0, s26, 0x160000
	s_addc_u32 s1, s27, 0
	s_mov_b32 m0, s29
	ds_read_b128 v[168:171], v181 offset:32768
	ds_read_b128 v[184:187], v181 offset:33792
	ds_read_b128 v[188:191], v181 offset:34816
	ds_read_b128 v[192:195], v181 offset:35840
	ds_read_b128 v[196:199], v181 offset:36864
	ds_read_b128 v[200:203], v181 offset:37888
	ds_read_b128 v[204:207], v181 offset:38912
	ds_read_b128 v[208:211], v181 offset:39936
	global_load_lds_dwordx4 v160, s[0:1]
	s_mov_b32 m0, s33
	s_nop 0
	global_load_lds_dwordx4 v162, s[0:1]
	s_waitcnt vmcnt(8) lgkmcnt(0)
	s_barrier
	v_mfma_f32_16x16x32_bf16 v[156:159], v[96:99], v[168:171], v[156:159]
	v_mfma_f32_16x16x32_bf16 v[152:155], v[104:107], v[168:171], v[152:155]
	v_mfma_f32_16x16x32_bf16 v[144:147], v[96:99], v[188:191], v[144:147]
	v_mfma_f32_16x16x32_bf16 v[136:139], v[104:107], v[188:191], v[136:139]
	v_mfma_f32_16x16x32_bf16 v[92:95], v[96:99], v[196:199], v[92:95]
	v_mfma_f32_16x16x32_bf16 v[88:91], v[104:107], v[196:199], v[88:91]
	v_mfma_f32_16x16x32_bf16 v[80:83], v[96:99], v[204:207], v[80:83]
	v_mfma_f32_16x16x32_bf16 v[72:75], v[104:107], v[204:207], v[72:75]
	v_mfma_f32_16x16x32_bf16 v[156:159], v[100:103], v[184:187], v[156:159]
	v_mfma_f32_16x16x32_bf16 v[152:155], v[108:111], v[184:187], v[152:155]
	v_mfma_f32_16x16x32_bf16 v[144:147], v[100:103], v[192:195], v[144:147]
	v_mfma_f32_16x16x32_bf16 v[136:139], v[108:111], v[192:195], v[136:139]
	v_mfma_f32_16x16x32_bf16 v[92:95], v[100:103], v[200:203], v[92:95]
	v_mfma_f32_16x16x32_bf16 v[88:91], v[108:111], v[200:203], v[88:91]
	v_mfma_f32_16x16x32_bf16 v[80:83], v[100:103], v[208:211], v[80:83]
	v_mfma_f32_16x16x32_bf16 v[72:75], v[108:111], v[208:211], v[72:75]
	v_mfma_f32_16x16x32_bf16 v[148:151], v[112:115], v[168:171], v[148:151]
	v_mfma_f32_16x16x32_bf16 v[140:143], v[120:123], v[168:171], v[140:143]
	v_mfma_f32_16x16x32_bf16 v[132:135], v[112:115], v[188:191], v[132:135]
	v_mfma_f32_16x16x32_bf16 v[128:131], v[120:123], v[188:191], v[128:131]
	v_mfma_f32_16x16x32_bf16 v[84:87], v[112:115], v[196:199], v[84:87]
	v_mfma_f32_16x16x32_bf16 v[76:79], v[120:123], v[196:199], v[76:79]
	v_mfma_f32_16x16x32_bf16 v[68:71], v[112:115], v[204:207], v[68:71]
	v_mfma_f32_16x16x32_bf16 v[64:67], v[120:123], v[204:207], v[64:67]
	v_mfma_f32_16x16x32_bf16 v[148:151], v[116:119], v[184:187], v[148:151]
	v_mfma_f32_16x16x32_bf16 v[140:143], v[124:127], v[184:187], v[140:143]
	v_mfma_f32_16x16x32_bf16 v[132:135], v[116:119], v[192:195], v[132:135]
	v_mfma_f32_16x16x32_bf16 v[128:131], v[124:127], v[192:195], v[128:131]
	v_mfma_f32_16x16x32_bf16 v[84:87], v[116:119], v[200:203], v[84:87]
	v_mfma_f32_16x16x32_bf16 v[76:79], v[124:127], v[200:203], v[76:79]
	v_mfma_f32_16x16x32_bf16 v[68:71], v[116:119], v[208:211], v[68:71]
	v_mfma_f32_16x16x32_bf16 v[64:67], v[124:127], v[208:211], v[64:67]
	s_barrier
	s_add_i32 s0, s52, s15
	v_lshl_add_u64 v[172:173], v[172:173], 0, s[10:11]
	s_mov_b32 m0, s0
	ds_read_b128 v[168:171], v181 offset:49152
	ds_read_b128 v[184:187], v181 offset:50176
	ds_read_b128 v[188:191], v181 offset:51200
	ds_read_b128 v[192:195], v181 offset:52224
	ds_read_b128 v[196:199], v181 offset:53248
	ds_read_b128 v[200:203], v181 offset:54272
	ds_read_b128 v[204:207], v181 offset:55296
	ds_read_b128 v[208:211], v181 offset:56320
	global_load_lds_dwordx4 v[172:173], off
	s_add_i32 m0, s0, 0x2000
	s_add_u32 s0, s24, 0x160080
	v_lshl_add_u64 v[172:173], v[212:213], 0, s[10:11]
	s_addc_u32 s1, s25, 0
	s_add_i32 s24, s53, s15
	global_load_lds_dwordx4 v[172:173], off
	s_mov_b32 m0, s24
	s_nop 0
	global_load_lds_dwordx4 v160, s[0:1]
	s_add_i32 m0, s24, 0x2000
	s_nop 0
	global_load_lds_dwordx4 v162, s[0:1]
	v_lshl_add_u64 v[172:173], v[214:215], 0, s[10:11]
	s_mov_b32 m0, s36
	s_nop 0
	global_load_lds_dwordx4 v[172:173], off
	v_lshl_add_u64 v[172:173], v[216:217], 0, s[10:11]
	s_mov_b32 m0, s37
	s_nop 0
	global_load_lds_dwordx4 v[172:173], off
	s_waitcnt vmcnt(8) lgkmcnt(0)
	s_barrier
	v_mfma_f32_16x16x32_bf16 v[60:63], v[96:99], v[168:171], v[60:63]
	v_mfma_f32_16x16x32_bf16 v[56:59], v[104:107], v[168:171], v[56:59]
	v_mfma_f32_16x16x32_bf16 v[48:51], v[96:99], v[188:191], v[48:51]
	v_mfma_f32_16x16x32_bf16 v[40:43], v[104:107], v[188:191], v[40:43]
	v_mfma_f32_16x16x32_bf16 v[28:31], v[96:99], v[196:199], v[28:31]
	v_mfma_f32_16x16x32_bf16 v[24:27], v[104:107], v[196:199], v[24:27]
	v_mfma_f32_16x16x32_bf16 v[16:19], v[96:99], v[204:207], v[16:19]
	v_mfma_f32_16x16x32_bf16 v[8:11], v[104:107], v[204:207], v[8:11]
	v_mfma_f32_16x16x32_bf16 v[60:63], v[100:103], v[184:187], v[60:63]
	v_mfma_f32_16x16x32_bf16 v[56:59], v[108:111], v[184:187], v[56:59]
	v_mfma_f32_16x16x32_bf16 v[48:51], v[100:103], v[192:195], v[48:51]
	v_mfma_f32_16x16x32_bf16 v[40:43], v[108:111], v[192:195], v[40:43]
	v_mfma_f32_16x16x32_bf16 v[28:31], v[100:103], v[200:203], v[28:31]
	v_mfma_f32_16x16x32_bf16 v[24:27], v[108:111], v[200:203], v[24:27]
	v_mfma_f32_16x16x32_bf16 v[16:19], v[100:103], v[208:211], v[16:19]
	v_mfma_f32_16x16x32_bf16 v[8:11], v[108:111], v[208:211], v[8:11]
	v_mfma_f32_16x16x32_bf16 v[52:55], v[112:115], v[168:171], v[52:55]
	v_mfma_f32_16x16x32_bf16 v[44:47], v[120:123], v[168:171], v[44:47]
	v_mfma_f32_16x16x32_bf16 v[36:39], v[112:115], v[188:191], v[36:39]
	v_mfma_f32_16x16x32_bf16 v[32:35], v[120:123], v[188:191], v[32:35]
	v_mfma_f32_16x16x32_bf16 v[20:23], v[112:115], v[196:199], v[20:23]
	v_mfma_f32_16x16x32_bf16 v[12:15], v[120:123], v[196:199], v[12:15]
	v_mfma_f32_16x16x32_bf16 v[4:7], v[112:115], v[204:207], v[4:7]
	v_mfma_f32_16x16x32_bf16 v[0:3], v[120:123], v[204:207], v[0:3]
	v_mfma_f32_16x16x32_bf16 v[52:55], v[116:119], v[184:187], v[52:55]
	v_mfma_f32_16x16x32_bf16 v[44:47], v[124:127], v[184:187], v[44:47]
	v_mfma_f32_16x16x32_bf16 v[36:39], v[116:119], v[192:195], v[36:39]
	v_mfma_f32_16x16x32_bf16 v[32:35], v[124:127], v[192:195], v[32:35]
	v_mfma_f32_16x16x32_bf16 v[20:23], v[116:119], v[200:203], v[20:23]
	v_mfma_f32_16x16x32_bf16 v[12:15], v[124:127], v[200:203], v[12:15]
	v_mfma_f32_16x16x32_bf16 v[4:7], v[116:119], v[208:211], v[4:7]
	v_mfma_f32_16x16x32_bf16 v[0:3], v[124:127], v[208:211], v[0:3]
	s_add_i32 s51, s51, 2
	s_add_u32 s49, s49, 0x100
	s_addc_u32 s50, s50, 0
	s_cmpk_gt_u32 s51, 0x55
	s_mov_b64 s[0:1], s[4:5]
	s_barrier
	s_cbranch_scc0 .LBB0_1120
	s_setprio 0
	s_and_b64 vcc, exec, s[12:13]
	s_cbranch_vccz .LBB0_1123
	s_barrier
